# adds cvt_pk scaling in the retention far-key stage loop and batched layernorm reductions in the conv unit
# speedup vs baseline: 1.0196x; 1.0080x over previous
.LBB0_882:
	s_and_b32 s16, s25, 1
	s_mul_i32 s17, s16, 0xc000
	v_add_u32_e32 v63, s17, v58
	v_add_u32_e32 v76, v60, v63
	ds_read_b64_tr_b16 v[64:65], v76 offset:0
	ds_read_b64_tr_b16 v[66:67], v76 offset:0x400
	v_add_u32_e32 v77, v61, v63
	ds_read_b64_tr_b16 v[68:69], v77 offset:0
	ds_read_b64_tr_b16 v[70:71], v77 offset:0x400
	v_add_u32_e32 v63, v62, v63
	ds_read_b64_tr_b16 v[72:73], v63 offset:0
	ds_read_b64_tr_b16 v[74:75], v63 offset:0x400
	s_waitcnt lgkmcnt(0)
	v_mfma_f32_32x32x16_bf16 v[0:15], v[64:67], v[68:71], v[0:15]
	v_mfma_f32_32x32x16_bf16 v[16:31], v[64:67], v[72:75], v[16:31]
	ds_read_b64_tr_b16 v[64:65], v76 offset:0x800
	ds_read_b64_tr_b16 v[66:67], v76 offset:0xc00
	ds_read_b64_tr_b16 v[68:69], v77 offset:0x800
	ds_read_b64_tr_b16 v[70:71], v77 offset:0xc00
	ds_read_b64_tr_b16 v[72:73], v63 offset:0x800
	ds_read_b64_tr_b16 v[74:75], v63 offset:0xc00
	s_waitcnt lgkmcnt(0)
	s_nop 0
	v_mfma_f32_32x32x16_bf16 v[0:15], v[64:67], v[68:71], v[0:15]
	v_mfma_f32_32x32x16_bf16 v[16:31], v[64:67], v[72:75], v[16:31]
	ds_read_b64_tr_b16 v[64:65], v76 offset:0x1000
	ds_read_b64_tr_b16 v[66:67], v76 offset:0x1400
	ds_read_b64_tr_b16 v[68:69], v77 offset:0x1000
	ds_read_b64_tr_b16 v[70:71], v77 offset:0x1400
	ds_read_b64_tr_b16 v[72:73], v63 offset:0x1000
	ds_read_b64_tr_b16 v[74:75], v63 offset:0x1400
	s_waitcnt lgkmcnt(0)
	s_nop 0
	v_mfma_f32_32x32x16_bf16 v[0:15], v[64:67], v[68:71], v[0:15]
	v_mfma_f32_32x32x16_bf16 v[16:31], v[64:67], v[72:75], v[16:31]
	ds_read_b64_tr_b16 v[64:65], v76 offset:0x1800
	ds_read_b64_tr_b16 v[66:67], v76 offset:0x1c00
	ds_read_b64_tr_b16 v[68:69], v77 offset:0x1800
	ds_read_b64_tr_b16 v[70:71], v77 offset:0x1c00
	ds_read_b64_tr_b16 v[72:73], v63 offset:0x1800
	ds_read_b64_tr_b16 v[74:75], v63 offset:0x1c00
	s_waitcnt lgkmcnt(0)
	s_nop 0
	v_mfma_f32_32x32x16_bf16 v[0:15], v[64:67], v[68:71], v[0:15]
	s_andn2_b64 vcc, exec, s[14:15]
	v_mfma_f32_32x32x16_bf16 v[16:31], v[64:67], v[72:75], v[16:31]
	s_cbranch_vccnz .LBB0_872
	s_waitcnt vmcnt(2)
	v_lshlrev_b32_e32 v68, 16, v36
	v_and_b32_e32 v69, 0xffff0000, v36
	v_lshlrev_b32_e32 v70, 16, v37
	v_and_b32_e32 v71, 0xffff0000, v37
	v_lshlrev_b32_e32 v72, 16, v38
	v_and_b32_e32 v73, 0xffff0000, v38
	v_lshlrev_b32_e32 v74, 16, v39
	v_and_b32_e32 v75, 0xffff0000, v39
	s_xor_b32 s14, s16, 1
	s_mul_i32 s14, s14, 0xc000
	v_add_u32_e32 v63, s14, v59
	v_pk_mul_f32 v[84:85], v[50:51], v[68:69] op_sel_hi:[0,1]
	v_pk_mul_f32 v[86:87], v[50:51], v[70:71] op_sel_hi:[0,1]
	v_pk_mul_f32 v[88:89], v[50:51], v[72:73] op_sel_hi:[0,1]
	v_pk_mul_f32 v[90:91], v[50:51], v[74:75] op_sel_hi:[0,1]
	v_cvt_pk_bf16_f32 v64, v84, v85
	v_cvt_pk_bf16_f32 v65, v86, v87
	v_cvt_pk_bf16_f32 v66, v88, v89
	v_cvt_pk_bf16_f32 v67, v90, v91
	s_waitcnt vmcnt(0)
	ds_write_b128 v63, v[32:35]
	ds_write_b128 v63, v[40:43] offset:8192
	ds_write_b128 v63, v[64:67] offset:16384
	v_lshlrev_b32_e32 v76, 16, v44
	v_and_b32_e32 v77, 0xffff0000, v44
	v_lshlrev_b32_e32 v78, 16, v45
	v_and_b32_e32 v79, 0xffff0000, v45
	v_lshlrev_b32_e32 v80, 16, v46
	v_and_b32_e32 v81, 0xffff0000, v46
	v_lshlrev_b32_e32 v82, 16, v47
	v_and_b32_e32 v83, 0xffff0000, v47
	v_pk_mul_f32 v[84:85], v[54:55], v[76:77] op_sel_hi:[0,1]
	v_pk_mul_f32 v[86:87], v[54:55], v[78:79] op_sel_hi:[0,1]
	v_pk_mul_f32 v[88:89], v[54:55], v[80:81] op_sel_hi:[0,1]
	v_pk_mul_f32 v[90:91], v[54:55], v[82:83] op_sel_hi:[0,1]
	v_cvt_pk_bf16_f32 v64, v84, v85
	v_cvt_pk_bf16_f32 v65, v86, v87
	v_cvt_pk_bf16_f32 v66, v88, v89
	v_cvt_pk_bf16_f32 v67, v90, v91
	ds_write_b128 v63, v[64:67] offset:24576
	v_pk_mul_f32 v[84:85], v[52:53], v[68:69] op_sel_hi:[0,1]
	v_pk_mul_f32 v[86:87], v[52:53], v[70:71] op_sel_hi:[0,1]
	v_pk_mul_f32 v[88:89], v[52:53], v[72:73] op_sel_hi:[0,1]
	v_pk_mul_f32 v[90:91], v[52:53], v[74:75] op_sel_hi:[0,1]
	v_cvt_pk_bf16_f32 v64, v84, v85
	v_cvt_pk_bf16_f32 v65, v86, v87
	v_cvt_pk_bf16_f32 v66, v88, v89
	v_cvt_pk_bf16_f32 v67, v90, v91
	ds_write_b128 v63, v[64:67] offset:32768
	v_pk_mul_f32 v[84:85], v[56:57], v[76:77] op_sel_hi:[0,1]
	v_pk_mul_f32 v[86:87], v[56:57], v[78:79] op_sel_hi:[0,1]
	v_pk_mul_f32 v[88:89], v[56:57], v[80:81] op_sel_hi:[0,1]
	v_pk_mul_f32 v[90:91], v[56:57], v[82:83] op_sel_hi:[0,1]
	v_cvt_pk_bf16_f32 v64, v84, v85
	v_cvt_pk_bf16_f32 v65, v86, v87
	v_cvt_pk_bf16_f32 v66, v88, v89
	v_cvt_pk_bf16_f32 v67, v90, v91
	ds_write_b128 v63, v[64:67] offset:40960
	s_branch .LBB0_872

.LBB0_997:
	s_or_b64 exec, exec, s[10:11]
	v_mov_b32_e32 v0, 2
	v_lshlrev_b32_sdwa v152, v0, v8 dst_sel:DWORD dst_unused:UNUSED_PAD src0_sel:DWORD src1_sel:BYTE_0
	v_lshl_add_u64 v[28:29], s[0:1], 0, v[152:153]
	v_add_co_u32_e32 v12, vcc, 0x1000, v28
	s_movk_i32 s10, 0x2000
	s_nop 0
	v_addc_co_u32_e32 v13, vcc, 0, v29, vcc
	s_waitcnt lgkmcnt(0)
	s_barrier
	global_load_dword v3, v152, s[0:1]
	global_load_dword v2, v152, s[0:1] offset:1024
	global_load_dword v1, v152, s[0:1] offset:2048
	global_load_dword v0, v152, s[0:1] offset:3072
	global_load_dword v7, v[12:13], off
	global_load_dword v6, v[12:13], off offset:1024
	global_load_dword v5, v[12:13], off offset:2048
	global_load_dword v4, v[12:13], off offset:3072
	v_add_co_u32_e32 v12, vcc, s10, v28
	s_movk_i32 s10, 0x3000
	s_nop 0
	v_addc_co_u32_e32 v13, vcc, 0, v29, vcc
	v_add_co_u32_e32 v20, vcc, s10, v28
	s_movk_i32 s10, 0x4000
	s_nop 0
	v_addc_co_u32_e32 v21, vcc, 0, v29, vcc
	v_add_co_u32_e32 v24, vcc, s10, v28
	s_movk_i32 s10, 0x5000
	s_nop 0
	v_addc_co_u32_e32 v25, vcc, 0, v29, vcc
	v_add_co_u32_e32 v30, vcc, s10, v28
	s_movk_i32 s10, 0x6000
	s_nop 0
	v_addc_co_u32_e32 v31, vcc, 0, v29, vcc
	v_add_co_u32_e32 v32, vcc, s10, v28
	s_movk_i32 s10, 0x7000
	s_nop 0
	v_addc_co_u32_e32 v33, vcc, 0, v29, vcc
	v_add_co_u32_e32 v36, vcc, s10, v28
	global_load_dword v18, v[20:21], off offset:-4096
	global_load_dword v17, v[12:13], off offset:1024
	global_load_dword v16, v[12:13], off offset:2048
	global_load_dword v15, v[12:13], off offset:3072
	global_load_dword v14, v[20:21], off
	s_nop 0
	global_load_dword v13, v[20:21], off offset:1024
	global_load_dword v12, v[20:21], off offset:2048
	global_load_dword v9, v[20:21], off offset:3072
	v_addc_co_u32_e32 v37, vcc, 0, v29, vcc
	global_load_dword v19, v[30:31], off offset:-4096
	global_load_dword v22, v[24:25], off offset:1024
	global_load_dword v21, v[24:25], off offset:2048
	global_load_dword v20, v[24:25], off offset:3072
	global_load_dword v26, v[30:31], off
	s_nop 0
	global_load_dword v25, v[30:31], off offset:1024
	global_load_dword v24, v[30:31], off offset:2048
	global_load_dword v23, v[30:31], off offset:3072
	global_load_dword v28, v[36:37], off offset:-4096
	s_nop 0
	global_load_dword v31, v[32:33], off offset:1024
	global_load_dword v30, v[32:33], off offset:2048
	global_load_dword v29, v[32:33], off offset:3072
	global_load_dword v34, v[36:37], off
	s_nop 0
	global_load_dword v33, v[36:37], off offset:1024
	global_load_dword v32, v[36:37], off offset:2048
	v_ashrrev_i32_e32 v27, 3, v8
	v_lshlrev_b32_sdwa v36, v229, v8 dst_sel:DWORD dst_unused:UNUSED_PAD src0_sel:DWORD src1_sel:BYTE_0
	v_and_b32_e32 v61, 0xffffffe0, v27
	v_add_u32_e32 v62, 0, v36
	v_lshl_add_u32 v78, v61, 9, v62
	v_or_b32_e32 v43, 1, v61
	ds_read_u16 v37, v78
	v_lshl_add_u32 v35, v43, 9, v62
	ds_read_u16 v38, v35
	v_or_b32_e32 v48, 3, v61
	v_or_b32_e32 v72, 6, v61
	v_or_b32_e32 v44, 2, v61
	s_waitcnt lgkmcnt(1)
	v_lshlrev_b32_e32 v45, 16, v37
	v_lshl_add_u32 v37, v48, 9, v62
	v_or_b32_e32 v49, 4, v61
	v_lshl_add_u32 v40, v72, 9, v62
	v_or_b32_e32 v73, 7, v61
	ds_read_u16 v37, v37
	ds_read_u16 v40, v40
	v_lshl_add_u32 v35, v44, 9, v62
	s_waitcnt lgkmcnt(2)
	v_lshlrev_b32_e32 v46, 16, v38
	v_lshl_add_u32 v38, v49, 9, v62
	v_lshl_add_u32 v41, v73, 9, v62
	ds_read_u16 v39, v35
	ds_read_u16 v38, v38
	ds_read_u16 v41, v41
	global_load_dword v35, v152, s[2:3]
	v_or_b32_e32 v50, 5, v61
	s_waitcnt lgkmcnt(2)
	v_lshlrev_b32_e32 v47, 16, v39
	v_lshl_add_u32 v39, v50, 9, v62
	ds_read_u16 v39, v39
	v_or_b32_e32 v60, 8, v61
	v_lshlrev_b32_e32 v74, 16, v37
	v_lshl_add_u32 v37, v60, 9, v62
	s_waitcnt lgkmcnt(2)
	v_lshlrev_b32_e32 v75, 16, v38
	s_waitcnt lgkmcnt(0)
	v_lshlrev_b32_e32 v76, 16, v39
	v_lshlrev_b32_e32 v77, 16, v40
	v_lshlrev_b32_e32 v79, 16, v41
	ds_read_u16 v37, v37
	ds_read_u16 v38, v78 offset:4608
	ds_read_u16 v39, v78 offset:5120
	ds_read_u16 v40, v78 offset:5632
	ds_read_u16 v41, v78 offset:6144
	v_or_b32_e32 v70, 16, v61
	s_waitcnt lgkmcnt(4)
	v_lshlrev_b32_e32 v80, 16, v37
	s_waitcnt lgkmcnt(3)
	v_lshlrev_b32_e32 v81, 16, v38
	s_waitcnt lgkmcnt(1)
	v_lshlrev_b32_e32 v83, 16, v40
	v_lshl_add_u32 v40, v70, 9, v62
	v_lshlrev_b32_e32 v82, 16, v39
	s_waitcnt lgkmcnt(0)
	v_lshlrev_b32_e32 v84, 16, v41
	ds_read_u16 v37, v78 offset:6656
	ds_read_u16 v38, v78 offset:7168
	ds_read_u16 v39, v78 offset:7680
	ds_read_u16 v40, v40
	ds_read_u16 v41, v78 offset:8704
	v_or_b32_e32 v51, 24, v61
	s_waitcnt lgkmcnt(4)
	v_lshlrev_b32_e32 v85, 16, v37
	s_waitcnt lgkmcnt(3)
	v_lshlrev_b32_e32 v86, 16, v38
	s_waitcnt lgkmcnt(2)
	v_lshlrev_b32_e32 v87, 16, v39
	s_waitcnt lgkmcnt(1)
	v_lshlrev_b32_e32 v71, 16, v40
	s_waitcnt lgkmcnt(0)
	v_lshlrev_b32_e32 v53, 16, v41
	ds_read_u16 v37, v78 offset:9216
	ds_read_u16 v38, v78 offset:9728
	ds_read_u16 v39, v78 offset:10240
	ds_read_u16 v40, v78 offset:10752
	ds_read_u16 v41, v78 offset:11264
	s_waitcnt lgkmcnt(4)
	v_lshlrev_b32_e32 v54, 16, v37
	s_waitcnt lgkmcnt(3)
	v_lshlrev_b32_e32 v55, 16, v38
	v_lshl_add_u32 v38, v51, 9, v62
	s_waitcnt lgkmcnt(2)
	v_lshlrev_b32_e32 v56, 16, v39
	s_waitcnt lgkmcnt(1)
	v_lshlrev_b32_e32 v57, 16, v40
	s_waitcnt lgkmcnt(0)
	v_lshlrev_b32_e32 v58, 16, v41
	ds_read_u16 v37, v78 offset:11776
	ds_read_u16 v38, v38
	ds_read_u16 v39, v78 offset:12800
	ds_read_u16 v40, v78 offset:13312
	ds_read_u16 v41, v78 offset:13824
	v_add_u32_e32 v36, v62, v36
	s_waitcnt lgkmcnt(3)
	v_lshlrev_b32_e32 v52, 16, v38
	s_waitcnt lgkmcnt(2)
	v_lshlrev_b32_e32 v63, 16, v39
	s_waitcnt lgkmcnt(1)
	v_lshlrev_b32_e32 v64, 16, v40
	v_mov_b32_e32 v40, 0x3e00
	v_lshl_or_b32 v40, v27, 9, v40
	v_lshlrev_b32_e32 v59, 16, v37
	ds_read_u16 v37, v78 offset:14336
	ds_read_u16 v38, v78 offset:14848
	ds_read_u16 v39, v78 offset:15360
	v_add_u32_e32 v40, v62, v40
	s_waitcnt lgkmcnt(3)
	v_lshlrev_b32_e32 v65, 16, v41
	ds_read_u16 v40, v40
	ds_read_u16 v41, v78 offset:16384
	s_waitcnt lgkmcnt(3)
	v_lshlrev_b32_e32 v67, 16, v38
	s_waitcnt lgkmcnt(2)
	v_lshlrev_b32_e32 v68, 16, v39
	v_lshlrev_b32_e32 v66, 16, v37
	s_waitcnt lgkmcnt(1)
	v_lshlrev_b32_e32 v69, 16, v40
	ds_read_u16 v38, v78 offset:16896
	ds_read_u16 v39, v78 offset:17408
	ds_read_u16 v40, v78 offset:17920
	ds_read_u16 v88, v78 offset:18432
	ds_read_u16 v89, v78 offset:18944
	s_waitcnt lgkmcnt(5)
	v_lshlrev_b32_e32 v37, 16, v41
	s_waitcnt lgkmcnt(3)
	v_lshlrev_b32_e32 v41, 16, v39
	v_lshl_add_u32 v43, v43, 10, v36
	s_waitcnt lgkmcnt(1)
	v_lshlrev_b32_e32 v39, 16, v88
	v_lshl_add_u32 v88, v61, 10, v36
	v_lshl_add_u32 v44, v44, 10, v36
	v_lshlrev_b32_e32 v42, 16, v38
	v_lshlrev_b32_e32 v40, 16, v40
	s_waitcnt lgkmcnt(0)
	v_lshlrev_b32_e32 v38, 16, v89
	v_lshl_add_u32 v60, v60, 10, v36
	v_lshl_add_u32 v70, v70, 10, v36
	v_lshl_add_u32 v51, v51, 10, v36
	s_add_u32 s8, s19, s8
	s_addc_u32 s9, 0, s9
	s_mov_b32 s10, 0
	s_waitcnt vmcnt(0)
	v_fma_f32 v45, v3, v45, v35
	v_fmac_f32_e32 v45, v2, v46
	v_fmac_f32_e32 v45, v1, v47
	v_fmac_f32_e32 v45, v0, v74
	v_fmac_f32_e32 v45, v7, v75
	v_fmac_f32_e32 v45, v6, v76
	v_fmac_f32_e32 v45, v5, v77
	v_fmac_f32_e32 v45, v4, v79
	v_fmac_f32_e32 v45, v18, v80
	v_fmac_f32_e32 v45, v17, v81
	v_fmac_f32_e32 v45, v16, v82
	v_fmac_f32_e32 v45, v15, v83
	v_fmac_f32_e32 v45, v14, v84
	v_fmac_f32_e32 v45, v13, v85
	v_fmac_f32_e32 v45, v12, v86
	v_fmac_f32_e32 v45, v9, v87
	v_fmac_f32_e32 v45, v19, v71
	v_fmac_f32_e32 v45, v22, v53
	v_fmac_f32_e32 v45, v21, v54
	v_fmac_f32_e32 v45, v20, v55
	v_fmac_f32_e32 v45, v26, v56
	v_fmac_f32_e32 v45, v25, v57
	v_fmac_f32_e32 v45, v24, v58
	v_fmac_f32_e32 v45, v23, v59
	v_fmac_f32_e32 v45, v28, v52
	v_fmac_f32_e32 v45, v31, v63
	v_fmac_f32_e32 v45, v30, v64
	v_fmac_f32_e32 v45, v29, v65
	v_fmac_f32_e32 v45, v34, v66
	v_fmac_f32_e32 v45, v33, v67
	v_fmac_f32_e32 v45, v32, v68
	ds_write_b32 v88, v45 offset:49152
	v_fma_f32 v45, v3, v46, v35
	v_fmac_f32_e32 v45, v2, v47
	v_fmac_f32_e32 v45, v1, v74
	v_fmac_f32_e32 v45, v0, v75
	v_fmac_f32_e32 v45, v7, v76
	v_fmac_f32_e32 v45, v6, v77
	v_fmac_f32_e32 v45, v5, v79
	v_fmac_f32_e32 v45, v4, v80
	v_fmac_f32_e32 v45, v18, v81
	v_fmac_f32_e32 v45, v17, v82
	v_fmac_f32_e32 v45, v16, v83
	v_fmac_f32_e32 v45, v15, v84
	v_fmac_f32_e32 v45, v14, v85
	v_fmac_f32_e32 v45, v13, v86
	v_fmac_f32_e32 v45, v12, v87
	v_fmac_f32_e32 v45, v9, v71
	v_fmac_f32_e32 v45, v19, v53
	v_fmac_f32_e32 v45, v22, v54
	v_fmac_f32_e32 v45, v21, v55
	v_fmac_f32_e32 v45, v20, v56
	v_fmac_f32_e32 v45, v26, v57
	v_fmac_f32_e32 v45, v25, v58
	v_fmac_f32_e32 v45, v24, v59
	v_fmac_f32_e32 v45, v23, v52
	v_fmac_f32_e32 v45, v28, v63
	v_fmac_f32_e32 v45, v31, v64
	v_fmac_f32_e32 v45, v30, v65
	v_fmac_f32_e32 v45, v29, v66
	v_fmac_f32_e32 v45, v34, v67
	v_fmac_f32_e32 v45, v33, v68
	v_fmac_f32_e32 v45, v32, v69
	ds_write_b32 v43, v45 offset:49152
	v_fma_f32 v43, v3, v47, v35
	v_fmac_f32_e32 v43, v2, v74
	v_fmac_f32_e32 v43, v1, v75
	v_fmac_f32_e32 v43, v0, v76
	v_fmac_f32_e32 v43, v7, v77
	v_fmac_f32_e32 v43, v6, v79
	v_fmac_f32_e32 v43, v5, v80
	v_fmac_f32_e32 v43, v4, v81
	v_fmac_f32_e32 v43, v18, v82
	v_fmac_f32_e32 v43, v17, v83
	v_fmac_f32_e32 v43, v16, v84
	v_fmac_f32_e32 v43, v15, v85
	v_fmac_f32_e32 v43, v14, v86
	v_fmac_f32_e32 v43, v13, v87
	v_fmac_f32_e32 v43, v12, v71
	v_fmac_f32_e32 v43, v9, v53
	v_fmac_f32_e32 v43, v19, v54
	v_fmac_f32_e32 v43, v22, v55
	v_fmac_f32_e32 v43, v21, v56
	v_fmac_f32_e32 v43, v20, v57
	v_fmac_f32_e32 v43, v26, v58
	v_fmac_f32_e32 v43, v25, v59
	v_fmac_f32_e32 v43, v24, v52
	v_fmac_f32_e32 v43, v23, v63
	v_fmac_f32_e32 v43, v28, v64
	v_fmac_f32_e32 v43, v31, v65
	v_fmac_f32_e32 v43, v30, v66
	v_fmac_f32_e32 v43, v29, v67
	v_fmac_f32_e32 v43, v34, v68
	v_fmac_f32_e32 v43, v33, v69
	v_fmac_f32_e32 v43, v32, v37
	ds_write_b32 v44, v43 offset:49152
	v_fma_f32 v43, v3, v74, v35
	v_fmac_f32_e32 v43, v2, v75
	v_fmac_f32_e32 v43, v1, v76
	v_fmac_f32_e32 v43, v0, v77
	v_fmac_f32_e32 v43, v7, v79
	v_fmac_f32_e32 v43, v6, v80
	v_fmac_f32_e32 v43, v5, v81
	v_fmac_f32_e32 v43, v4, v82
	v_fmac_f32_e32 v43, v18, v83
	v_fmac_f32_e32 v43, v17, v84
	v_fmac_f32_e32 v43, v16, v85
	v_fmac_f32_e32 v43, v15, v86
	v_fmac_f32_e32 v43, v14, v87
	v_fmac_f32_e32 v43, v13, v71
	v_fmac_f32_e32 v43, v12, v53
	v_fmac_f32_e32 v43, v9, v54
	v_fmac_f32_e32 v43, v19, v55
	v_fmac_f32_e32 v43, v22, v56
	v_fmac_f32_e32 v43, v21, v57
	v_fmac_f32_e32 v43, v20, v58
	v_fmac_f32_e32 v43, v26, v59
	v_fmac_f32_e32 v43, v25, v52
	v_fmac_f32_e32 v43, v24, v63
	v_fmac_f32_e32 v43, v23, v64
	v_fmac_f32_e32 v43, v28, v65
	v_fmac_f32_e32 v43, v31, v66
	v_fmac_f32_e32 v43, v30, v67
	v_fmac_f32_e32 v43, v29, v68
	v_fmac_f32_e32 v43, v34, v69
	v_fmac_f32_e32 v43, v33, v37
	v_fmac_f32_e32 v43, v32, v42
	v_lshl_add_u32 v44, v48, 10, v36
	ds_write_b32 v44, v43 offset:49152
	v_fma_f32 v43, v3, v75, v35
	v_fmac_f32_e32 v43, v2, v76
	v_fmac_f32_e32 v43, v1, v77
	v_fmac_f32_e32 v43, v0, v79
	v_fmac_f32_e32 v43, v7, v80
	v_fmac_f32_e32 v43, v6, v81
	v_fmac_f32_e32 v43, v5, v82
	v_fmac_f32_e32 v43, v4, v83
	v_fmac_f32_e32 v43, v18, v84
	v_fmac_f32_e32 v43, v17, v85
	v_fmac_f32_e32 v43, v16, v86
	v_fmac_f32_e32 v43, v15, v87
	v_fmac_f32_e32 v43, v14, v71
	v_fmac_f32_e32 v43, v13, v53
	v_fmac_f32_e32 v43, v12, v54
	v_fmac_f32_e32 v43, v9, v55
	v_fmac_f32_e32 v43, v19, v56
	v_fmac_f32_e32 v43, v22, v57
	v_fmac_f32_e32 v43, v21, v58
	v_fmac_f32_e32 v43, v20, v59
	v_fmac_f32_e32 v43, v26, v52
	v_fmac_f32_e32 v43, v25, v63
	v_fmac_f32_e32 v43, v24, v64
	v_fmac_f32_e32 v43, v23, v65
	v_fmac_f32_e32 v43, v28, v66
	v_fmac_f32_e32 v43, v31, v67
	v_fmac_f32_e32 v43, v30, v68
	v_fmac_f32_e32 v43, v29, v69
	v_fmac_f32_e32 v43, v34, v37
	v_fmac_f32_e32 v43, v33, v42
	v_fmac_f32_e32 v43, v32, v41
	v_lshl_add_u32 v44, v49, 10, v36
	ds_write_b32 v44, v43 offset:49152
	v_fma_f32 v43, v3, v76, v35
	v_fmac_f32_e32 v43, v2, v77
	v_fmac_f32_e32 v43, v1, v79
	v_fmac_f32_e32 v43, v0, v80
	v_fmac_f32_e32 v43, v7, v81
	v_fmac_f32_e32 v43, v6, v82
	v_fmac_f32_e32 v43, v5, v83
	v_fmac_f32_e32 v43, v4, v84
	v_fmac_f32_e32 v43, v18, v85
	v_fmac_f32_e32 v43, v17, v86
	v_fmac_f32_e32 v43, v16, v87
	v_fmac_f32_e32 v43, v15, v71
	v_fmac_f32_e32 v43, v14, v53
	v_fmac_f32_e32 v43, v13, v54
	v_fmac_f32_e32 v43, v12, v55
	v_fmac_f32_e32 v43, v9, v56
	v_fmac_f32_e32 v43, v19, v57
	v_fmac_f32_e32 v43, v22, v58
	v_fmac_f32_e32 v43, v21, v59
	v_fmac_f32_e32 v43, v20, v52
	v_fmac_f32_e32 v43, v26, v63
	v_fmac_f32_e32 v43, v25, v64
	v_fmac_f32_e32 v43, v24, v65
	v_fmac_f32_e32 v43, v23, v66
	v_fmac_f32_e32 v43, v28, v67
	v_fmac_f32_e32 v43, v31, v68
	v_fmac_f32_e32 v43, v30, v69
	v_fmac_f32_e32 v43, v29, v37
	v_fmac_f32_e32 v43, v34, v42
	v_fmac_f32_e32 v43, v33, v41
	v_fmac_f32_e32 v43, v32, v40
	v_lshl_add_u32 v44, v50, 10, v36
	ds_write_b32 v44, v43 offset:49152
	v_fma_f32 v43, v3, v77, v35
	v_fmac_f32_e32 v43, v2, v79
	v_fmac_f32_e32 v43, v1, v80
	v_fmac_f32_e32 v43, v0, v81
	v_fmac_f32_e32 v43, v7, v82
	v_fmac_f32_e32 v43, v6, v83
	v_fmac_f32_e32 v43, v5, v84
	v_fmac_f32_e32 v43, v4, v85
	v_fmac_f32_e32 v43, v18, v86
	v_fmac_f32_e32 v43, v17, v87
	v_fmac_f32_e32 v43, v16, v71
	v_fmac_f32_e32 v43, v15, v53
	v_fmac_f32_e32 v43, v14, v54
	v_fmac_f32_e32 v43, v13, v55
	v_fmac_f32_e32 v43, v12, v56
	v_fmac_f32_e32 v43, v9, v57
	v_fmac_f32_e32 v43, v19, v58
	v_fmac_f32_e32 v43, v22, v59
	v_fmac_f32_e32 v43, v21, v52
	v_fmac_f32_e32 v43, v20, v63
	v_fmac_f32_e32 v43, v26, v64
	v_fmac_f32_e32 v43, v25, v65
	v_fmac_f32_e32 v43, v24, v66
	v_fmac_f32_e32 v43, v23, v67
	v_fmac_f32_e32 v43, v28, v68
	v_fmac_f32_e32 v43, v31, v69
	v_fmac_f32_e32 v43, v30, v37
	v_fmac_f32_e32 v43, v29, v42
	v_fmac_f32_e32 v43, v34, v41
	v_fmac_f32_e32 v43, v33, v40
	v_fmac_f32_e32 v43, v32, v39
	v_lshl_add_u32 v44, v72, 10, v36
	ds_write_b32 v44, v43 offset:49152
	v_fma_f32 v43, v3, v79, v35
	v_fmac_f32_e32 v43, v2, v80
	v_fmac_f32_e32 v43, v1, v81
	v_fmac_f32_e32 v43, v0, v82
	v_fmac_f32_e32 v43, v7, v83
	v_fmac_f32_e32 v43, v6, v84
	v_fmac_f32_e32 v43, v5, v85
	v_fmac_f32_e32 v43, v4, v86
	v_fmac_f32_e32 v43, v18, v87
	v_fmac_f32_e32 v43, v17, v71
	v_fmac_f32_e32 v43, v16, v53
	v_fmac_f32_e32 v43, v15, v54
	v_fmac_f32_e32 v43, v14, v55
	v_fmac_f32_e32 v43, v13, v56
	v_fmac_f32_e32 v43, v12, v57
	v_fmac_f32_e32 v43, v9, v58
	v_fmac_f32_e32 v43, v19, v59
	v_fmac_f32_e32 v43, v22, v52
	v_fmac_f32_e32 v43, v21, v63
	v_fmac_f32_e32 v43, v20, v64
	v_fmac_f32_e32 v43, v26, v65
	v_fmac_f32_e32 v43, v25, v66
	v_fmac_f32_e32 v43, v24, v67
	v_fmac_f32_e32 v43, v23, v68
	v_fmac_f32_e32 v43, v28, v69
	v_fmac_f32_e32 v43, v31, v37
	v_or_b32_e32 v74, 9, v61
	v_fmac_f32_e32 v43, v30, v42
	v_lshl_add_u32 v44, v74, 9, v62
	v_or_b32_e32 v75, 10, v61
	v_fmac_f32_e32 v43, v29, v41
	ds_read_u16 v44, v44
	v_lshl_add_u32 v45, v75, 9, v62
	v_fmac_f32_e32 v43, v34, v40
	ds_read_u16 v45, v45
	v_fmac_f32_e32 v43, v33, v39
	v_fmac_f32_e32 v43, v32, v38
	v_lshl_add_u32 v46, v73, 10, v36
	v_or_b32_e32 v77, 11, v61
	v_or_b32_e32 v82, 14, v61
	ds_write_b32 v46, v43 offset:49152
	v_lshl_add_u32 v43, v77, 9, v62
	v_or_b32_e32 v79, 12, v61
	v_lshl_add_u32 v46, v82, 9, v62
	v_or_b32_e32 v81, 13, v61
	ds_read_u16 v46, v46
	ds_read_u16 v43, v43
	s_waitcnt lgkmcnt(4)
	v_lshlrev_b32_e32 v73, 16, v44
	v_lshl_add_u32 v44, v79, 9, v62
	s_waitcnt lgkmcnt(3)
	v_lshlrev_b32_e32 v76, 16, v45
	ds_read_u16 v44, v44
	v_lshl_add_u32 v45, v81, 9, v62
	ds_read_u16 v45, v45
	v_or_b32_e32 v83, 15, v61
	v_lshl_add_u32 v47, v83, 9, v62
	v_fma_f32 v80, v3, v80, v35
	ds_read_u16 v47, v47
	v_fmac_f32_e32 v80, v2, v73
	s_waitcnt lgkmcnt(3)
	v_lshlrev_b32_e32 v84, 16, v43
	v_fmac_f32_e32 v80, v1, v76
	s_waitcnt lgkmcnt(2)
	v_lshlrev_b32_e32 v85, 16, v44
	v_fmac_f32_e32 v80, v0, v84
	s_waitcnt lgkmcnt(1)
	v_lshlrev_b32_e32 v86, 16, v45
	v_fmac_f32_e32 v80, v7, v85
	v_lshlrev_b32_e32 v87, 16, v46
	v_fmac_f32_e32 v80, v6, v86
	s_waitcnt lgkmcnt(0)
	v_lshlrev_b32_e32 v88, 16, v47
	ds_read_u16 v43, v78 offset:8192
	ds_read_u16 v44, v78 offset:12288
	ds_read_u16 v45, v78 offset:19456
	ds_read_u16 v46, v78 offset:19968
	ds_read_u16 v48, v78 offset:20480
	v_fmac_f32_e32 v80, v5, v87
	s_waitcnt lgkmcnt(4)
	v_lshlrev_b32_e32 v89, 16, v43
	v_fmac_f32_e32 v80, v4, v88
	v_fmac_f32_e32 v80, v18, v89
	v_fmac_f32_e32 v80, v17, v53
	v_fmac_f32_e32 v80, v16, v54
	v_fmac_f32_e32 v80, v15, v55
	v_fmac_f32_e32 v80, v14, v56
	v_fmac_f32_e32 v80, v13, v57
	v_fmac_f32_e32 v80, v12, v58
	s_waitcnt lgkmcnt(3)
	v_lshlrev_b32_e32 v72, 16, v44
	v_fmac_f32_e32 v80, v9, v59
	v_fmac_f32_e32 v80, v19, v72
	v_fmac_f32_e32 v80, v22, v63
	v_fmac_f32_e32 v80, v21, v64
	v_fmac_f32_e32 v80, v20, v65
	v_fmac_f32_e32 v80, v26, v66
	v_fmac_f32_e32 v80, v25, v67
	v_fmac_f32_e32 v80, v24, v68
	v_fmac_f32_e32 v80, v23, v69
	v_fmac_f32_e32 v80, v28, v37
	v_fmac_f32_e32 v80, v31, v42
	v_fmac_f32_e32 v80, v30, v41
	v_fmac_f32_e32 v80, v29, v40
	v_fmac_f32_e32 v80, v34, v39
	s_waitcnt lgkmcnt(2)
	v_lshlrev_b32_e32 v47, 16, v45
	v_fmac_f32_e32 v80, v33, v38
	v_fmac_f32_e32 v80, v32, v47
	s_waitcnt lgkmcnt(1)
	v_lshlrev_b32_e32 v45, 16, v46
	s_waitcnt lgkmcnt(0)
	v_lshlrev_b32_e32 v43, 16, v48
	ds_read_u16 v44, v78 offset:20992
	ds_read_u16 v46, v78 offset:21504
	ds_read_u16 v48, v78 offset:22016
	ds_read_u16 v90, v78 offset:22528
	ds_read_u16 v91, v78 offset:23040
	ds_write_b32 v60, v80 offset:49152
	v_fma_f32 v60, v3, v73, v35
	v_fmac_f32_e32 v60, v2, v76
	v_fmac_f32_e32 v60, v1, v84
	v_fmac_f32_e32 v60, v0, v85
	v_fmac_f32_e32 v60, v7, v86
	v_fmac_f32_e32 v60, v6, v87
	v_fmac_f32_e32 v60, v5, v88
	v_fmac_f32_e32 v60, v4, v89
	v_fmac_f32_e32 v60, v18, v53
	v_fmac_f32_e32 v60, v17, v54
	v_fmac_f32_e32 v60, v16, v55
	v_fmac_f32_e32 v60, v15, v56
	v_fmac_f32_e32 v60, v14, v57
	v_fmac_f32_e32 v60, v13, v58
	v_fmac_f32_e32 v60, v12, v59
	v_fmac_f32_e32 v60, v9, v72
	v_fmac_f32_e32 v60, v19, v63
	v_fmac_f32_e32 v60, v22, v64
	v_fmac_f32_e32 v60, v21, v65
	v_fmac_f32_e32 v60, v20, v66
	v_fmac_f32_e32 v60, v26, v67
	v_fmac_f32_e32 v60, v25, v68
	v_fmac_f32_e32 v60, v24, v69
	v_fmac_f32_e32 v60, v23, v37
	v_fmac_f32_e32 v60, v28, v42
	v_fmac_f32_e32 v60, v31, v41
	v_fmac_f32_e32 v60, v30, v40
	v_fmac_f32_e32 v60, v29, v39
	v_fmac_f32_e32 v60, v34, v38
	v_fmac_f32_e32 v60, v33, v47
	v_fmac_f32_e32 v60, v32, v45
	v_lshl_add_u32 v73, v74, 10, v36
	ds_write_b32 v73, v60 offset:49152
	v_fma_f32 v60, v3, v76, v35
	v_fmac_f32_e32 v60, v2, v84
	v_fmac_f32_e32 v60, v1, v85
	v_fmac_f32_e32 v60, v0, v86
	v_fmac_f32_e32 v60, v7, v87
	v_fmac_f32_e32 v60, v6, v88
	v_fmac_f32_e32 v60, v5, v89
	v_fmac_f32_e32 v60, v4, v53
	v_fmac_f32_e32 v60, v18, v54
	v_fmac_f32_e32 v60, v17, v55
	v_fmac_f32_e32 v60, v16, v56
	v_fmac_f32_e32 v60, v15, v57
	v_fmac_f32_e32 v60, v14, v58
	v_fmac_f32_e32 v60, v13, v59
	v_fmac_f32_e32 v60, v12, v72
	v_fmac_f32_e32 v60, v9, v63
	v_fmac_f32_e32 v60, v19, v64
	v_fmac_f32_e32 v60, v22, v65
	v_fmac_f32_e32 v60, v21, v66
	v_fmac_f32_e32 v60, v20, v67
	v_fmac_f32_e32 v60, v26, v68
	v_fmac_f32_e32 v60, v25, v69
	v_fmac_f32_e32 v60, v24, v37
	v_fmac_f32_e32 v60, v23, v42
	v_fmac_f32_e32 v60, v28, v41
	v_fmac_f32_e32 v60, v31, v40
	v_fmac_f32_e32 v60, v30, v39
	v_fmac_f32_e32 v60, v29, v38
	v_fmac_f32_e32 v60, v34, v47
	v_fmac_f32_e32 v60, v33, v45
	v_fmac_f32_e32 v60, v32, v43
	v_lshl_add_u32 v73, v75, 10, v36
	ds_write_b32 v73, v60 offset:49152
	v_fma_f32 v60, v3, v84, v35
	v_fmac_f32_e32 v60, v2, v85
	v_fmac_f32_e32 v60, v1, v86
	v_fmac_f32_e32 v60, v0, v87
	v_fmac_f32_e32 v60, v7, v88
	v_fmac_f32_e32 v60, v6, v89
	v_fmac_f32_e32 v60, v5, v53
	v_fmac_f32_e32 v60, v4, v54
	v_fmac_f32_e32 v60, v18, v55
	v_fmac_f32_e32 v60, v17, v56
	v_fmac_f32_e32 v60, v16, v57
	v_fmac_f32_e32 v60, v15, v58
	v_fmac_f32_e32 v60, v14, v59
	v_fmac_f32_e32 v60, v13, v72
	v_fmac_f32_e32 v60, v12, v63
	v_fmac_f32_e32 v60, v9, v64
	v_fmac_f32_e32 v60, v19, v65
	v_fmac_f32_e32 v60, v22, v66
	v_fmac_f32_e32 v60, v21, v67
	v_fmac_f32_e32 v60, v20, v68
	v_fmac_f32_e32 v60, v26, v69
	v_fmac_f32_e32 v60, v25, v37
	v_fmac_f32_e32 v60, v24, v42
	v_fmac_f32_e32 v60, v23, v41
	v_fmac_f32_e32 v60, v28, v40
	v_fmac_f32_e32 v60, v31, v39
	v_fmac_f32_e32 v60, v30, v38
	v_fmac_f32_e32 v60, v29, v47
	v_fmac_f32_e32 v60, v34, v45
	s_waitcnt lgkmcnt(7)
	v_lshlrev_b32_e32 v50, 16, v44
	v_fmac_f32_e32 v60, v33, v43
	v_fmac_f32_e32 v60, v32, v50
	v_lshl_add_u32 v73, v77, 10, v36
	ds_write_b32 v73, v60 offset:49152
	v_fma_f32 v60, v3, v85, v35
	v_fmac_f32_e32 v60, v2, v86
	v_fmac_f32_e32 v60, v1, v87
	v_fmac_f32_e32 v60, v0, v88
	v_fmac_f32_e32 v60, v7, v89
	v_fmac_f32_e32 v60, v6, v53
	v_fmac_f32_e32 v60, v5, v54
	v_fmac_f32_e32 v60, v4, v55
	v_fmac_f32_e32 v60, v18, v56
	v_fmac_f32_e32 v60, v17, v57
	v_fmac_f32_e32 v60, v16, v58
	v_fmac_f32_e32 v60, v15, v59
	v_fmac_f32_e32 v60, v14, v72
	v_fmac_f32_e32 v60, v13, v63
	v_fmac_f32_e32 v60, v12, v64
	v_fmac_f32_e32 v60, v9, v65
	v_fmac_f32_e32 v60, v19, v66
	v_fmac_f32_e32 v60, v22, v67
	v_fmac_f32_e32 v60, v21, v68
	v_fmac_f32_e32 v60, v20, v69
	v_fmac_f32_e32 v60, v26, v37
	v_fmac_f32_e32 v60, v25, v42
	v_fmac_f32_e32 v60, v24, v41
	v_fmac_f32_e32 v60, v23, v40
	v_fmac_f32_e32 v60, v28, v39
	v_fmac_f32_e32 v60, v31, v38
	v_fmac_f32_e32 v60, v30, v47
	v_fmac_f32_e32 v60, v29, v45
	v_fmac_f32_e32 v60, v34, v43
	s_waitcnt lgkmcnt(7)
	v_lshlrev_b32_e32 v49, 16, v46
	v_fmac_f32_e32 v60, v33, v50
	v_fmac_f32_e32 v60, v32, v49
	v_lshl_add_u32 v73, v79, 10, v36
	ds_write_b32 v73, v60 offset:49152
	v_fma_f32 v60, v3, v86, v35
	v_fmac_f32_e32 v60, v2, v87
	v_fmac_f32_e32 v60, v1, v88
	v_fmac_f32_e32 v60, v0, v89
	v_fmac_f32_e32 v60, v7, v53
	v_fmac_f32_e32 v60, v6, v54
	v_fmac_f32_e32 v60, v5, v55
	v_fmac_f32_e32 v60, v4, v56
	v_fmac_f32_e32 v60, v18, v57
	v_fmac_f32_e32 v60, v17, v58
	v_fmac_f32_e32 v60, v16, v59
	v_fmac_f32_e32 v60, v15, v72
	v_fmac_f32_e32 v60, v14, v63
	v_fmac_f32_e32 v60, v13, v64
	v_fmac_f32_e32 v60, v12, v65
	v_fmac_f32_e32 v60, v9, v66
	v_fmac_f32_e32 v60, v19, v67
	v_fmac_f32_e32 v60, v22, v68
	v_fmac_f32_e32 v60, v21, v69
	v_fmac_f32_e32 v60, v20, v37
	v_fmac_f32_e32 v60, v26, v42
	v_fmac_f32_e32 v60, v25, v41
	v_fmac_f32_e32 v60, v24, v40
	v_fmac_f32_e32 v60, v23, v39
	v_fmac_f32_e32 v60, v28, v38
	v_fmac_f32_e32 v60, v31, v47
	v_fmac_f32_e32 v60, v30, v45
	v_fmac_f32_e32 v60, v29, v43
	v_fmac_f32_e32 v60, v34, v50
	s_waitcnt lgkmcnt(7)
	v_lshlrev_b32_e32 v48, 16, v48
	v_fmac_f32_e32 v60, v33, v49
	v_fmac_f32_e32 v60, v32, v48
	v_lshl_add_u32 v73, v81, 10, v36
	ds_write_b32 v73, v60 offset:49152
	v_fma_f32 v60, v3, v87, v35
	v_fmac_f32_e32 v60, v2, v88
	v_fmac_f32_e32 v60, v1, v89
	v_fmac_f32_e32 v60, v0, v53
	v_fmac_f32_e32 v60, v7, v54
	v_fmac_f32_e32 v60, v6, v55
	v_fmac_f32_e32 v60, v5, v56
	v_fmac_f32_e32 v60, v4, v57
	v_fmac_f32_e32 v60, v18, v58
	v_fmac_f32_e32 v60, v17, v59
	v_fmac_f32_e32 v60, v16, v72
	v_fmac_f32_e32 v60, v15, v63
	v_fmac_f32_e32 v60, v14, v64
	v_fmac_f32_e32 v60, v13, v65
	v_fmac_f32_e32 v60, v12, v66
	v_fmac_f32_e32 v60, v9, v67
	v_fmac_f32_e32 v60, v19, v68
	v_fmac_f32_e32 v60, v22, v69
	v_fmac_f32_e32 v60, v21, v37
	v_fmac_f32_e32 v60, v20, v42
	v_fmac_f32_e32 v60, v26, v41
	v_fmac_f32_e32 v60, v25, v40
	v_fmac_f32_e32 v60, v24, v39
	v_fmac_f32_e32 v60, v23, v38
	v_fmac_f32_e32 v60, v28, v47
	v_fmac_f32_e32 v60, v31, v45
	v_fmac_f32_e32 v60, v30, v43
	v_fmac_f32_e32 v60, v29, v50
	v_fmac_f32_e32 v60, v34, v49
	s_waitcnt lgkmcnt(7)
	v_lshlrev_b32_e32 v46, 16, v90
	v_fmac_f32_e32 v60, v33, v48
	v_fmac_f32_e32 v60, v32, v46
	v_lshl_add_u32 v73, v82, 10, v36
	ds_write_b32 v73, v60 offset:49152
	v_fma_f32 v60, v3, v88, v35
	v_fmac_f32_e32 v60, v2, v89
	v_fmac_f32_e32 v60, v1, v53
	v_fmac_f32_e32 v60, v0, v54
	v_fmac_f32_e32 v60, v7, v55
	v_fmac_f32_e32 v60, v6, v56
	v_fmac_f32_e32 v60, v5, v57
	v_fmac_f32_e32 v60, v4, v58
	v_fmac_f32_e32 v60, v18, v59
	v_fmac_f32_e32 v60, v17, v72
	v_fmac_f32_e32 v60, v16, v63
	v_fmac_f32_e32 v60, v15, v64
	v_fmac_f32_e32 v60, v14, v65
	v_fmac_f32_e32 v60, v13, v66
	v_fmac_f32_e32 v60, v12, v67
	v_fmac_f32_e32 v60, v9, v68
	v_fmac_f32_e32 v60, v19, v69
	v_fmac_f32_e32 v60, v22, v37
	v_fmac_f32_e32 v60, v21, v42
	v_fmac_f32_e32 v60, v20, v41
	v_fmac_f32_e32 v60, v26, v40
	v_fmac_f32_e32 v60, v25, v39
	v_fmac_f32_e32 v60, v24, v38
	v_fmac_f32_e32 v60, v23, v47
	v_fmac_f32_e32 v60, v28, v45
	v_fmac_f32_e32 v60, v31, v43
	v_fmac_f32_e32 v60, v30, v50
	v_fmac_f32_e32 v60, v29, v49
	v_fmac_f32_e32 v60, v34, v48
	s_waitcnt lgkmcnt(7)
	v_lshlrev_b32_e32 v44, 16, v91
	v_fmac_f32_e32 v60, v33, v46
	v_fmac_f32_e32 v60, v32, v44
	v_lshl_add_u32 v53, v83, 10, v36
	v_or_b32_e32 v73, 17, v61
	ds_write_b32 v53, v60 offset:49152
	v_lshl_add_u32 v53, v73, 9, v62
	ds_read_u16 v53, v53
	v_or_b32_e32 v74, 18, v61
	v_lshl_add_u32 v54, v74, 9, v62
	v_or_b32_e32 v75, 19, v61
	ds_read_u16 v54, v54
	v_lshl_add_u32 v55, v75, 9, v62
	v_or_b32_e32 v76, 20, v61
	ds_read_u16 v55, v55
	v_lshl_add_u32 v56, v76, 9, v62
	v_or_b32_e32 v77, 21, v61
	ds_read_u16 v56, v56
	v_lshl_add_u32 v57, v77, 9, v62
	v_or_b32_e32 v84, 22, v61
	ds_read_u16 v57, v57
	s_waitcnt lgkmcnt(4)
	v_lshlrev_b32_e32 v79, 16, v53
	v_lshl_add_u32 v53, v84, 9, v62
	ds_read_u16 v53, v53
	v_fma_f32 v71, v3, v71, v35
	s_waitcnt lgkmcnt(4)
	v_lshlrev_b32_e32 v80, 16, v54
	v_fmac_f32_e32 v71, v2, v79
	s_waitcnt lgkmcnt(3)
	v_lshlrev_b32_e32 v81, 16, v55
	v_or_b32_e32 v85, 23, v61
	v_fmac_f32_e32 v71, v1, v80
	s_waitcnt lgkmcnt(2)
	v_lshlrev_b32_e32 v82, 16, v56
	v_lshl_add_u32 v54, v85, 9, v62
	v_fmac_f32_e32 v71, v0, v81
	s_waitcnt lgkmcnt(1)
	v_lshlrev_b32_e32 v83, 16, v57
	ds_read_u16 v54, v54
	ds_read_u16 v55, v78 offset:23552
	ds_read_u16 v56, v78 offset:24064
	ds_read_u16 v58, v78 offset:24576
	v_fmac_f32_e32 v71, v7, v82
	s_waitcnt lgkmcnt(4)
	v_lshlrev_b32_e32 v86, 16, v53
	v_fmac_f32_e32 v71, v6, v83
	s_waitcnt lgkmcnt(3)
	v_lshlrev_b32_e32 v87, 16, v54
	v_fmac_f32_e32 v71, v5, v86
	v_fmac_f32_e32 v71, v4, v87
	v_fmac_f32_e32 v71, v18, v72
	v_fmac_f32_e32 v71, v17, v63
	v_fmac_f32_e32 v71, v16, v64
	v_fmac_f32_e32 v71, v15, v65
	v_fmac_f32_e32 v71, v14, v66
	v_fmac_f32_e32 v71, v13, v67
	v_fmac_f32_e32 v71, v12, v68
	v_fmac_f32_e32 v71, v9, v69
	v_fmac_f32_e32 v71, v19, v37
	v_fmac_f32_e32 v71, v22, v42
	v_fmac_f32_e32 v71, v21, v41
	v_fmac_f32_e32 v71, v20, v40
	v_fmac_f32_e32 v71, v26, v39
	v_fmac_f32_e32 v71, v25, v38
	v_fmac_f32_e32 v71, v24, v47
	v_fmac_f32_e32 v71, v23, v45
	v_fmac_f32_e32 v71, v28, v43
	v_fmac_f32_e32 v71, v31, v50
	v_fmac_f32_e32 v71, v30, v49
	v_fmac_f32_e32 v71, v29, v48
	v_fmac_f32_e32 v71, v34, v46
	s_waitcnt lgkmcnt(2)
	v_lshlrev_b32_e32 v57, 16, v55
	v_fmac_f32_e32 v71, v33, v44
	v_fmac_f32_e32 v71, v32, v57
	s_waitcnt lgkmcnt(1)
	v_lshlrev_b32_e32 v55, 16, v56
	s_waitcnt lgkmcnt(0)
	v_lshlrev_b32_e32 v53, 16, v58
	ds_read_u16 v54, v78 offset:25088
	ds_read_u16 v56, v78 offset:25600
	ds_read_u16 v58, v78 offset:26112
	ds_read_u16 v88, v78 offset:26624
	ds_read_u16 v89, v78 offset:27136
	ds_write_b32 v70, v71 offset:49152
	v_fma_f32 v70, v3, v79, v35
	v_fmac_f32_e32 v70, v2, v80
	v_fmac_f32_e32 v70, v1, v81
	v_fmac_f32_e32 v70, v0, v82
	v_fmac_f32_e32 v70, v7, v83
	v_fmac_f32_e32 v70, v6, v86
	v_fmac_f32_e32 v70, v5, v87
	v_fmac_f32_e32 v70, v4, v72
	v_fmac_f32_e32 v70, v18, v63
	v_fmac_f32_e32 v70, v17, v64
	v_fmac_f32_e32 v70, v16, v65
	v_fmac_f32_e32 v70, v15, v66
	v_fmac_f32_e32 v70, v14, v67
	v_fmac_f32_e32 v70, v13, v68
	v_fmac_f32_e32 v70, v12, v69
	v_fmac_f32_e32 v70, v9, v37
	v_fmac_f32_e32 v70, v19, v42
	v_fmac_f32_e32 v70, v22, v41
	v_fmac_f32_e32 v70, v21, v40
	v_fmac_f32_e32 v70, v20, v39
	v_fmac_f32_e32 v70, v26, v38
	v_fmac_f32_e32 v70, v25, v47
	v_fmac_f32_e32 v70, v24, v45
	v_fmac_f32_e32 v70, v23, v43
	v_fmac_f32_e32 v70, v28, v50
	v_fmac_f32_e32 v70, v31, v49
	v_fmac_f32_e32 v70, v30, v48
	v_fmac_f32_e32 v70, v29, v46
	v_fmac_f32_e32 v70, v34, v44
	v_fmac_f32_e32 v70, v33, v57
	v_fmac_f32_e32 v70, v32, v55
	v_lshl_add_u32 v71, v73, 10, v36
	ds_write_b32 v71, v70 offset:49152
	v_fma_f32 v70, v3, v80, v35
	v_fmac_f32_e32 v70, v2, v81
	v_fmac_f32_e32 v70, v1, v82
	v_fmac_f32_e32 v70, v0, v83
	v_fmac_f32_e32 v70, v7, v86
	v_fmac_f32_e32 v70, v6, v87
	v_fmac_f32_e32 v70, v5, v72
	v_fmac_f32_e32 v70, v4, v63
	v_fmac_f32_e32 v70, v18, v64
	v_fmac_f32_e32 v70, v17, v65
	v_fmac_f32_e32 v70, v16, v66
	v_fmac_f32_e32 v70, v15, v67
	v_fmac_f32_e32 v70, v14, v68
	v_fmac_f32_e32 v70, v13, v69
	v_fmac_f32_e32 v70, v12, v37
	v_fmac_f32_e32 v70, v9, v42
	v_fmac_f32_e32 v70, v19, v41
	v_fmac_f32_e32 v70, v22, v40
	v_fmac_f32_e32 v70, v21, v39
	v_fmac_f32_e32 v70, v20, v38
	v_fmac_f32_e32 v70, v26, v47
	v_fmac_f32_e32 v70, v25, v45
	v_fmac_f32_e32 v70, v24, v43
	v_fmac_f32_e32 v70, v23, v50
	v_fmac_f32_e32 v70, v28, v49
	v_fmac_f32_e32 v70, v31, v48
	v_fmac_f32_e32 v70, v30, v46
	v_fmac_f32_e32 v70, v29, v44
	v_fmac_f32_e32 v70, v34, v57
	v_fmac_f32_e32 v70, v33, v55
	v_fmac_f32_e32 v70, v32, v53
	v_lshl_add_u32 v71, v74, 10, v36
	ds_write_b32 v71, v70 offset:49152
	v_fma_f32 v70, v3, v81, v35
	v_fmac_f32_e32 v70, v2, v82
	v_fmac_f32_e32 v70, v1, v83
	v_fmac_f32_e32 v70, v0, v86
	v_fmac_f32_e32 v70, v7, v87
	v_fmac_f32_e32 v70, v6, v72
	v_fmac_f32_e32 v70, v5, v63
	v_fmac_f32_e32 v70, v4, v64
	v_fmac_f32_e32 v70, v18, v65
	v_fmac_f32_e32 v70, v17, v66
	v_fmac_f32_e32 v70, v16, v67
	v_fmac_f32_e32 v70, v15, v68
	v_fmac_f32_e32 v70, v14, v69
	v_fmac_f32_e32 v70, v13, v37
	v_fmac_f32_e32 v70, v12, v42
	v_fmac_f32_e32 v70, v9, v41
	v_fmac_f32_e32 v70, v19, v40
	v_fmac_f32_e32 v70, v22, v39
	v_fmac_f32_e32 v70, v21, v38
	v_fmac_f32_e32 v70, v20, v47
	v_fmac_f32_e32 v70, v26, v45
	v_fmac_f32_e32 v70, v25, v43
	v_fmac_f32_e32 v70, v24, v50
	v_fmac_f32_e32 v70, v23, v49
	v_fmac_f32_e32 v70, v28, v48
	v_fmac_f32_e32 v70, v31, v46
	v_fmac_f32_e32 v70, v30, v44
	v_fmac_f32_e32 v70, v29, v57
	v_fmac_f32_e32 v70, v34, v55
	s_waitcnt lgkmcnt(7)
	v_lshlrev_b32_e32 v60, 16, v54
	v_fmac_f32_e32 v70, v33, v53
	v_fmac_f32_e32 v70, v32, v60
	v_lshl_add_u32 v71, v75, 10, v36
	ds_write_b32 v71, v70 offset:49152
	v_fma_f32 v70, v3, v82, v35
	v_fmac_f32_e32 v70, v2, v83
	v_fmac_f32_e32 v70, v1, v86
	v_fmac_f32_e32 v70, v0, v87
	v_fmac_f32_e32 v70, v7, v72
	v_fmac_f32_e32 v70, v6, v63
	v_fmac_f32_e32 v70, v5, v64
	v_fmac_f32_e32 v70, v4, v65
	v_fmac_f32_e32 v70, v18, v66
	v_fmac_f32_e32 v70, v17, v67
	v_fmac_f32_e32 v70, v16, v68
	v_fmac_f32_e32 v70, v15, v69
	v_fmac_f32_e32 v70, v14, v37
	v_fmac_f32_e32 v70, v13, v42
	v_fmac_f32_e32 v70, v12, v41
	v_fmac_f32_e32 v70, v9, v40
	v_fmac_f32_e32 v70, v19, v39
	v_fmac_f32_e32 v70, v22, v38
	v_fmac_f32_e32 v70, v21, v47
	v_fmac_f32_e32 v70, v20, v45
	v_fmac_f32_e32 v70, v26, v43
	v_fmac_f32_e32 v70, v25, v50
	v_fmac_f32_e32 v70, v24, v49
	v_fmac_f32_e32 v70, v23, v48
	v_fmac_f32_e32 v70, v28, v46
	v_fmac_f32_e32 v70, v31, v44
	v_fmac_f32_e32 v70, v30, v57
	v_fmac_f32_e32 v70, v29, v55
	v_fmac_f32_e32 v70, v34, v53
	s_waitcnt lgkmcnt(7)
	v_lshlrev_b32_e32 v59, 16, v56
	v_fmac_f32_e32 v70, v33, v60
	v_fmac_f32_e32 v70, v32, v59
	v_lshl_add_u32 v71, v76, 10, v36
	ds_write_b32 v71, v70 offset:49152
	v_fma_f32 v70, v3, v83, v35
	v_fmac_f32_e32 v70, v2, v86
	v_fmac_f32_e32 v70, v1, v87
	v_fmac_f32_e32 v70, v0, v72
	v_fmac_f32_e32 v70, v7, v63
	v_fmac_f32_e32 v70, v6, v64
	v_fmac_f32_e32 v70, v5, v65
	v_fmac_f32_e32 v70, v4, v66
	v_fmac_f32_e32 v70, v18, v67
	v_fmac_f32_e32 v70, v17, v68
	v_fmac_f32_e32 v70, v16, v69
	v_fmac_f32_e32 v70, v15, v37
	v_fmac_f32_e32 v70, v14, v42
	v_fmac_f32_e32 v70, v13, v41
	v_fmac_f32_e32 v70, v12, v40
	v_fmac_f32_e32 v70, v9, v39
	v_fmac_f32_e32 v70, v19, v38
	v_fmac_f32_e32 v70, v22, v47
	v_fmac_f32_e32 v70, v21, v45
	v_fmac_f32_e32 v70, v20, v43
	v_fmac_f32_e32 v70, v26, v50
	v_fmac_f32_e32 v70, v25, v49
	v_fmac_f32_e32 v70, v24, v48
	v_fmac_f32_e32 v70, v23, v46
	v_fmac_f32_e32 v70, v28, v44
	v_fmac_f32_e32 v70, v31, v57
	v_fmac_f32_e32 v70, v30, v55
	v_fmac_f32_e32 v70, v29, v53
	v_fmac_f32_e32 v70, v34, v60
	s_waitcnt lgkmcnt(7)
	v_lshlrev_b32_e32 v58, 16, v58
	v_fmac_f32_e32 v70, v33, v59
	v_fmac_f32_e32 v70, v32, v58
	v_lshl_add_u32 v71, v77, 10, v36
	ds_write_b32 v71, v70 offset:49152
	v_fma_f32 v70, v3, v86, v35
	v_fmac_f32_e32 v70, v2, v87
	v_fmac_f32_e32 v70, v1, v72
	v_fmac_f32_e32 v70, v0, v63
	v_fmac_f32_e32 v70, v7, v64
	v_fmac_f32_e32 v70, v6, v65
	v_fmac_f32_e32 v70, v5, v66
	v_fmac_f32_e32 v70, v4, v67
	v_fmac_f32_e32 v70, v18, v68
	v_fmac_f32_e32 v70, v17, v69
	v_fmac_f32_e32 v70, v16, v37
	v_fmac_f32_e32 v70, v15, v42
	v_fmac_f32_e32 v70, v14, v41
	v_fmac_f32_e32 v70, v13, v40
	v_fmac_f32_e32 v70, v12, v39
	v_fmac_f32_e32 v70, v9, v38
	v_fmac_f32_e32 v70, v19, v47
	v_fmac_f32_e32 v70, v22, v45
	v_fmac_f32_e32 v70, v21, v43
	v_fmac_f32_e32 v70, v20, v50
	v_fmac_f32_e32 v70, v26, v49
	v_fmac_f32_e32 v70, v25, v48
	v_fmac_f32_e32 v70, v24, v46
	v_fmac_f32_e32 v70, v23, v44
	v_fmac_f32_e32 v70, v28, v57
	v_fmac_f32_e32 v70, v31, v55
	v_fmac_f32_e32 v70, v30, v53
	v_fmac_f32_e32 v70, v29, v60
	v_fmac_f32_e32 v70, v34, v59
	s_waitcnt lgkmcnt(7)
	v_lshlrev_b32_e32 v56, 16, v88
	v_fmac_f32_e32 v70, v33, v58
	v_fmac_f32_e32 v70, v32, v56
	v_lshl_add_u32 v71, v84, 10, v36
	ds_write_b32 v71, v70 offset:49152
	v_fma_f32 v70, v3, v87, v35
	v_fmac_f32_e32 v70, v2, v72
	v_fmac_f32_e32 v70, v1, v63
	v_fmac_f32_e32 v70, v0, v64
	v_fmac_f32_e32 v70, v7, v65
	v_fmac_f32_e32 v70, v6, v66
	v_fmac_f32_e32 v70, v5, v67
	v_fmac_f32_e32 v70, v4, v68
	v_fmac_f32_e32 v70, v18, v69
	v_fmac_f32_e32 v70, v17, v37
	v_fmac_f32_e32 v70, v16, v42
	v_fmac_f32_e32 v70, v15, v41
	v_fmac_f32_e32 v70, v14, v40
	v_fmac_f32_e32 v70, v13, v39
	v_fmac_f32_e32 v70, v12, v38
	v_fmac_f32_e32 v70, v9, v47
	v_fmac_f32_e32 v70, v19, v45
	v_fmac_f32_e32 v70, v22, v43
	v_fmac_f32_e32 v70, v21, v50
	v_fmac_f32_e32 v70, v20, v49
	v_fmac_f32_e32 v70, v26, v48
	v_fmac_f32_e32 v70, v25, v46
	v_fmac_f32_e32 v70, v24, v44
	v_fmac_f32_e32 v70, v23, v57
	v_fmac_f32_e32 v70, v28, v55
	v_fmac_f32_e32 v70, v31, v53
	v_fmac_f32_e32 v70, v30, v60
	v_fmac_f32_e32 v70, v29, v59
	v_fmac_f32_e32 v70, v34, v58
	s_waitcnt lgkmcnt(7)
	v_lshlrev_b32_e32 v54, 16, v89
	v_fmac_f32_e32 v70, v33, v56
	v_fmac_f32_e32 v70, v32, v54
	v_lshl_add_u32 v63, v85, 10, v36
	v_or_b32_e32 v75, 25, v61
	v_or_b32_e32 v71, 27, v61
	ds_write_b32 v63, v70 offset:49152
	v_lshl_add_u32 v63, v75, 9, v62
	v_lshl_add_u32 v65, v71, 9, v62
	ds_read_u16 v63, v63
	ds_read_u16 v65, v65
	v_or_b32_e32 v73, 26, v61
	v_lshl_add_u32 v64, v73, 9, v62
	ds_read_u16 v64, v64
	v_or_b32_e32 v69, 28, v61
	v_or_b32_e32 v67, 29, v61
	v_lshl_add_u32 v66, v69, 9, v62
	v_lshl_add_u32 v68, v67, 9, v62
	ds_read_u16 v66, v66
	ds_read_u16 v68, v68
	s_waitcnt lgkmcnt(3)
	v_lshlrev_b32_e32 v74, 16, v65
	v_or_b32_e32 v65, 30, v61
	v_lshl_add_u32 v61, v65, 9, v62
	v_lshlrev_b32_e32 v77, 16, v63
	ds_read_u16 v63, v61
	v_fma_f32 v52, v3, v52, v35
	s_waitcnt lgkmcnt(3)
	v_lshlrev_b32_e32 v76, 16, v64
	v_fmac_f32_e32 v52, v2, v77
	v_or_b32_e32 v61, 31, v27
	v_fmac_f32_e32 v52, v1, v76
	s_waitcnt lgkmcnt(2)
	v_lshlrev_b32_e32 v72, 16, v66
	v_lshl_add_u32 v62, v61, 9, v62
	v_fmac_f32_e32 v52, v0, v74
	s_waitcnt lgkmcnt(1)
	v_lshlrev_b32_e32 v70, 16, v68
	ds_read_u16 v62, v62
	ds_read_u16 v64, v78 offset:27648
	ds_read_u16 v79, v78 offset:28160
	ds_read_u16 v80, v78 offset:28672
	v_fmac_f32_e32 v52, v7, v72
	s_waitcnt lgkmcnt(4)
	v_lshlrev_b32_e32 v68, 16, v63
	v_fmac_f32_e32 v52, v6, v70
	s_waitcnt lgkmcnt(3)
	v_lshlrev_b32_e32 v66, 16, v62
	v_fmac_f32_e32 v52, v5, v68
	v_fmac_f32_e32 v52, v4, v66
	v_fmac_f32_e32 v52, v18, v37
	v_fmac_f32_e32 v52, v17, v42
	v_fmac_f32_e32 v52, v16, v41
	v_fmac_f32_e32 v52, v15, v40
	v_fmac_f32_e32 v52, v14, v39
	v_fmac_f32_e32 v52, v13, v38
	v_fmac_f32_e32 v52, v12, v47
	v_fmac_f32_e32 v52, v9, v45
	v_fmac_f32_e32 v52, v19, v43
	v_fmac_f32_e32 v52, v22, v50
	v_fmac_f32_e32 v52, v21, v49
	v_fmac_f32_e32 v52, v20, v48
	v_fmac_f32_e32 v52, v26, v46
	v_fmac_f32_e32 v52, v25, v44
	v_fmac_f32_e32 v52, v24, v57
	v_fmac_f32_e32 v52, v23, v55
	v_fmac_f32_e32 v52, v28, v53
	v_fmac_f32_e32 v52, v31, v60
	v_fmac_f32_e32 v52, v30, v59
	v_fmac_f32_e32 v52, v29, v58
	v_fmac_f32_e32 v52, v34, v56
	s_waitcnt lgkmcnt(2)
	v_lshlrev_b32_e32 v64, 16, v64
	v_fmac_f32_e32 v52, v33, v54
	v_fmac_f32_e32 v52, v32, v64
	s_waitcnt lgkmcnt(1)
	v_lshlrev_b32_e32 v63, 16, v79
	s_waitcnt lgkmcnt(0)
	v_lshlrev_b32_e32 v62, 16, v80
	ds_read_u16 v79, v78 offset:29184
	ds_read_u16 v80, v78 offset:29696
	ds_read_u16 v81, v78 offset:30208
	ds_read_u16 v82, v78 offset:30720
	ds_read_u16 v78, v78 offset:31232
	ds_write_b32 v51, v52 offset:49152
	v_fma_f32 v51, v3, v77, v35
	v_fmac_f32_e32 v51, v2, v76
	v_fmac_f32_e32 v51, v1, v74
	v_fmac_f32_e32 v51, v0, v72
	v_fmac_f32_e32 v51, v7, v70
	v_fmac_f32_e32 v51, v6, v68
	v_fmac_f32_e32 v51, v5, v66
	v_fmac_f32_e32 v51, v4, v37
	v_fmac_f32_e32 v51, v18, v42
	v_fmac_f32_e32 v51, v17, v41
	v_fmac_f32_e32 v51, v16, v40
	v_fmac_f32_e32 v51, v15, v39
	v_fmac_f32_e32 v51, v14, v38
	v_fmac_f32_e32 v51, v13, v47
	v_fmac_f32_e32 v51, v12, v45
	v_fmac_f32_e32 v51, v9, v43
	v_fmac_f32_e32 v51, v19, v50
	v_fmac_f32_e32 v51, v22, v49
	v_fmac_f32_e32 v51, v21, v48
	v_fmac_f32_e32 v51, v20, v46
	v_fmac_f32_e32 v51, v26, v44
	v_fmac_f32_e32 v51, v25, v57
	v_fmac_f32_e32 v51, v24, v55
	v_fmac_f32_e32 v51, v23, v53
	v_fmac_f32_e32 v51, v28, v60
	v_fmac_f32_e32 v51, v31, v59
	v_fmac_f32_e32 v51, v30, v58
	v_fmac_f32_e32 v51, v29, v56
	v_fmac_f32_e32 v51, v34, v54
	v_fmac_f32_e32 v51, v33, v64
	v_fmac_f32_e32 v51, v32, v63
	v_lshl_add_u32 v52, v75, 10, v36
	ds_write_b32 v52, v51 offset:49152
	v_fma_f32 v51, v3, v76, v35
	v_fmac_f32_e32 v51, v2, v74
	v_fmac_f32_e32 v51, v1, v72
	v_fmac_f32_e32 v51, v0, v70
	v_fmac_f32_e32 v51, v7, v68
	v_fmac_f32_e32 v51, v6, v66
	v_fmac_f32_e32 v51, v5, v37
	v_fmac_f32_e32 v51, v4, v42
	v_fmac_f32_e32 v51, v18, v41
	v_fmac_f32_e32 v51, v17, v40
	v_fmac_f32_e32 v51, v16, v39
	v_fmac_f32_e32 v51, v15, v38
	v_fmac_f32_e32 v51, v14, v47
	v_fmac_f32_e32 v51, v13, v45
	v_fmac_f32_e32 v51, v12, v43
	v_fmac_f32_e32 v51, v9, v50
	v_fmac_f32_e32 v51, v19, v49
	v_fmac_f32_e32 v51, v22, v48
	v_fmac_f32_e32 v51, v21, v46
	v_fmac_f32_e32 v51, v20, v44
	v_fmac_f32_e32 v51, v26, v57
	v_fmac_f32_e32 v51, v25, v55
	v_fmac_f32_e32 v51, v24, v53
	v_fmac_f32_e32 v51, v23, v60
	v_fmac_f32_e32 v51, v28, v59
	v_fmac_f32_e32 v51, v31, v58
	v_fmac_f32_e32 v51, v30, v56
	v_fmac_f32_e32 v51, v29, v54
	v_fmac_f32_e32 v51, v34, v64
	v_fmac_f32_e32 v51, v33, v63
	v_fmac_f32_e32 v51, v32, v62
	v_lshl_add_u32 v52, v73, 10, v36
	ds_write_b32 v52, v51 offset:49152
	v_fma_f32 v51, v3, v74, v35
	v_fmac_f32_e32 v51, v2, v72
	v_fmac_f32_e32 v51, v1, v70
	v_fmac_f32_e32 v51, v0, v68
	v_fmac_f32_e32 v51, v7, v66
	v_fmac_f32_e32 v51, v6, v37
	v_fmac_f32_e32 v51, v5, v42
	v_fmac_f32_e32 v51, v4, v41
	v_fmac_f32_e32 v51, v18, v40
	v_fmac_f32_e32 v51, v17, v39
	v_fmac_f32_e32 v51, v16, v38
	v_fmac_f32_e32 v51, v15, v47
	v_fmac_f32_e32 v51, v14, v45
	v_fmac_f32_e32 v51, v13, v43
	v_fmac_f32_e32 v51, v12, v50
	v_fmac_f32_e32 v51, v9, v49
	v_fmac_f32_e32 v51, v19, v48
	v_fmac_f32_e32 v51, v22, v46
	v_fmac_f32_e32 v51, v21, v44
	v_fmac_f32_e32 v51, v20, v57
	v_fmac_f32_e32 v51, v26, v55
	v_fmac_f32_e32 v51, v25, v53
	v_fmac_f32_e32 v51, v24, v60
	v_fmac_f32_e32 v51, v23, v59
	v_fmac_f32_e32 v51, v28, v58
	v_fmac_f32_e32 v51, v31, v56
	v_fmac_f32_e32 v51, v30, v54
	v_fmac_f32_e32 v51, v29, v64
	v_fmac_f32_e32 v51, v34, v63
	s_waitcnt lgkmcnt(7)
	v_lshlrev_b32_e32 v84, 16, v79
	v_fmac_f32_e32 v51, v33, v62
	v_fmac_f32_e32 v51, v32, v84
	v_lshl_add_u32 v52, v71, 10, v36
	ds_write_b32 v52, v51 offset:49152
	v_fma_f32 v51, v3, v72, v35
	v_fmac_f32_e32 v51, v2, v70
	v_fmac_f32_e32 v51, v1, v68
	v_fmac_f32_e32 v51, v0, v66
	v_fmac_f32_e32 v51, v7, v37
	v_fmac_f32_e32 v51, v6, v42
	v_fmac_f32_e32 v51, v5, v41
	v_fmac_f32_e32 v51, v4, v40
	v_fmac_f32_e32 v51, v18, v39
	v_fmac_f32_e32 v51, v17, v38
	v_fmac_f32_e32 v51, v16, v47
	v_fmac_f32_e32 v51, v15, v45
	v_fmac_f32_e32 v51, v14, v43
	v_fmac_f32_e32 v51, v13, v50
	v_fmac_f32_e32 v51, v12, v49
	v_fmac_f32_e32 v51, v9, v48
	v_fmac_f32_e32 v51, v19, v46
	v_fmac_f32_e32 v51, v22, v44
	v_fmac_f32_e32 v51, v21, v57
	v_fmac_f32_e32 v51, v20, v55
	v_fmac_f32_e32 v51, v26, v53
	v_fmac_f32_e32 v51, v25, v60
	v_fmac_f32_e32 v51, v24, v59
	v_fmac_f32_e32 v51, v23, v58
	v_fmac_f32_e32 v51, v28, v56
	v_fmac_f32_e32 v51, v31, v54
	v_fmac_f32_e32 v51, v30, v64
	v_fmac_f32_e32 v51, v29, v63
	v_fmac_f32_e32 v51, v34, v62
	s_waitcnt lgkmcnt(7)
	v_lshlrev_b32_e32 v83, 16, v80
	v_fmac_f32_e32 v51, v33, v84
	v_fmac_f32_e32 v51, v32, v83
	v_lshl_add_u32 v52, v69, 10, v36
	ds_write_b32 v52, v51 offset:49152
	v_fma_f32 v51, v3, v70, v35
	v_fmac_f32_e32 v51, v2, v68
	v_fmac_f32_e32 v51, v1, v66
	v_fmac_f32_e32 v51, v0, v37
	v_fmac_f32_e32 v51, v7, v42
	v_fmac_f32_e32 v51, v6, v41
	v_fmac_f32_e32 v51, v5, v40
	v_fmac_f32_e32 v51, v4, v39
	v_fmac_f32_e32 v51, v18, v38
	v_fmac_f32_e32 v51, v17, v47
	v_fmac_f32_e32 v51, v16, v45
	v_fmac_f32_e32 v51, v15, v43
	v_fmac_f32_e32 v51, v14, v50
	v_fmac_f32_e32 v51, v13, v49
	v_fmac_f32_e32 v51, v12, v48
	v_fmac_f32_e32 v51, v9, v46
	v_fmac_f32_e32 v51, v19, v44
	v_fmac_f32_e32 v51, v22, v57
	v_fmac_f32_e32 v51, v21, v55
	v_fmac_f32_e32 v51, v20, v53
	v_fmac_f32_e32 v51, v26, v60
	v_fmac_f32_e32 v51, v25, v59
	v_fmac_f32_e32 v51, v24, v58
	v_fmac_f32_e32 v51, v23, v56
	v_fmac_f32_e32 v51, v28, v54
	v_fmac_f32_e32 v51, v31, v64
	v_fmac_f32_e32 v51, v30, v63
	v_fmac_f32_e32 v51, v29, v62
	v_fmac_f32_e32 v51, v34, v84
	s_waitcnt lgkmcnt(7)
	v_lshlrev_b32_e32 v80, 16, v81
	v_fmac_f32_e32 v51, v33, v83
	v_fmac_f32_e32 v51, v32, v80
	v_lshl_add_u32 v52, v67, 10, v36
	ds_write_b32 v52, v51 offset:49152
	v_fma_f32 v51, v3, v68, v35
	v_fmac_f32_e32 v35, v3, v66
	v_fmac_f32_e32 v51, v2, v66
	v_fmac_f32_e32 v35, v2, v37
	v_fmac_f32_e32 v51, v1, v37
	v_fmac_f32_e32 v35, v1, v42
	v_fmac_f32_e32 v51, v0, v42
	v_fmac_f32_e32 v35, v0, v41
	v_fmac_f32_e32 v51, v7, v41
	v_fmac_f32_e32 v35, v7, v40
	v_fmac_f32_e32 v51, v6, v40
	v_fmac_f32_e32 v35, v6, v39
	v_fmac_f32_e32 v51, v5, v39
	v_fmac_f32_e32 v35, v5, v38
	v_fmac_f32_e32 v51, v4, v38
	v_fmac_f32_e32 v35, v4, v47
	v_fmac_f32_e32 v51, v18, v47
	v_fmac_f32_e32 v35, v18, v45
	v_fmac_f32_e32 v51, v17, v45
	v_fmac_f32_e32 v35, v17, v43
	v_fmac_f32_e32 v51, v16, v43
	v_fmac_f32_e32 v35, v16, v50
	v_fmac_f32_e32 v51, v15, v50
	v_fmac_f32_e32 v35, v15, v49
	v_fmac_f32_e32 v51, v14, v49
	v_fmac_f32_e32 v35, v14, v48
	v_fmac_f32_e32 v51, v13, v48
	v_fmac_f32_e32 v35, v13, v46
	v_fmac_f32_e32 v51, v12, v46
	v_fmac_f32_e32 v35, v12, v44
	v_fmac_f32_e32 v51, v9, v44
	v_fmac_f32_e32 v35, v9, v57
	v_fmac_f32_e32 v51, v19, v57
	v_fmac_f32_e32 v35, v19, v55
	v_fmac_f32_e32 v51, v22, v55
	v_fmac_f32_e32 v35, v22, v53
	v_fmac_f32_e32 v51, v21, v53
	v_fmac_f32_e32 v35, v21, v60
	v_fmac_f32_e32 v51, v20, v60
	v_fmac_f32_e32 v35, v20, v59
	v_fmac_f32_e32 v51, v26, v59
	v_fmac_f32_e32 v35, v26, v58
	v_fmac_f32_e32 v51, v25, v58
	v_fmac_f32_e32 v35, v25, v56
	v_fmac_f32_e32 v51, v24, v56
	v_fmac_f32_e32 v35, v24, v54
	v_fmac_f32_e32 v51, v23, v54
	v_fmac_f32_e32 v35, v23, v64
	v_fmac_f32_e32 v51, v28, v64
	v_fmac_f32_e32 v35, v28, v63
	v_fmac_f32_e32 v51, v31, v63
	v_fmac_f32_e32 v35, v31, v62
	v_fmac_f32_e32 v51, v30, v62
	v_fmac_f32_e32 v35, v30, v84
	v_fmac_f32_e32 v51, v29, v84
	v_fmac_f32_e32 v35, v29, v83
	s_waitcnt lgkmcnt(7)
	v_lshlrev_b32_e32 v79, 16, v82
	v_fmac_f32_e32 v51, v34, v83
	v_fmac_f32_e32 v35, v34, v80
	s_waitcnt lgkmcnt(6)
	v_lshlrev_b32_e32 v78, 16, v78
	v_fmac_f32_e32 v51, v33, v80
	v_fmac_f32_e32 v35, v33, v79
	v_fmac_f32_e32 v51, v32, v79
	v_lshl_add_u32 v52, v65, 10, v36
	v_fmac_f32_e32 v35, v32, v78
	v_lshl_add_u32 v0, v61, 10, v36
	ds_write_b32 v52, v51 offset:49152
	ds_write_b32 v0, v35 offset:49152
	v_lshlrev_b32_e32 v0, 4, v8
	v_and_b32_e32 v4, 0x3f0, v0
	s_waitcnt lgkmcnt(0)
	s_barrier
	global_load_dwordx4 v[0:3], v4, s[4:5]
	s_nop 0
	global_load_dwordx4 v[4:7], v4, s[6:7]
	v_and_b32_e32 v12, -8, v27
	v_ashrrev_i32_e32 v13, 31, v12
	v_lshl_add_u64 v[12:13], s[8:9], 0, v[12:13]
	v_lshlrev_b64 v[12:13], 11, v[12:13]
	v_and_b32_e32 v14, 63, v8
	v_lshl_or_b32 v12, v14, 3, v12
	v_lshl_add_u64 v[8:9], s[24:25], 0, v[12:13]
	v_lshlrev_b32_e32 v12, 10, v27
	v_lshlrev_b32_e32 v13, 4, v14
	s_movk_i32 s8, 0xe000
	v_and_or_b32 v12, v12, s8, v13
	s_add_i32 s8, 0, 0xc000
	v_add_u32_e32 v12, s8, v12
	s_waitcnt vmcnt(0)
	ds_read_b128 v[28:31], v12
	ds_read_b128 v[32:35], v12 offset:1024
	ds_read_b128 v[38:41], v12 offset:2048
	ds_read_b128 v[44:47], v12 offset:3072
	ds_read_b128 v[54:57], v12 offset:4096
	ds_read_b128 v[62:65], v12 offset:5120
	ds_read_b128 v[78:81], v12 offset:6144
	ds_read_b128 v[88:91], v12 offset:7168
	s_mov_b64 s[8:9], 0x800
	s_waitcnt lgkmcnt(0)
	v_add_f32_e32 v48, v29, v28
	v_add_f32_e32 v53, v30, v31
	v_add_f32_e32 v13, v48, v53
	v_add_f32_e32 v48, v33, v32
	v_add_f32_e32 v53, v34, v35
	v_add_f32_e32 v14, v48, v53
	v_add_f32_e32 v48, v39, v38
	v_add_f32_e32 v53, v40, v41
	v_add_f32_e32 v15, v48, v53
	v_add_f32_e32 v48, v45, v44
	v_add_f32_e32 v53, v46, v47
	v_add_f32_e32 v16, v48, v53
	v_add_f32_e32 v48, v55, v54
	v_add_f32_e32 v53, v56, v57
	v_add_f32_e32 v17, v48, v53
	v_add_f32_e32 v48, v63, v62
	v_add_f32_e32 v53, v64, v65
	v_add_f32_e32 v18, v48, v53
	v_add_f32_e32 v48, v79, v78
	v_add_f32_e32 v53, v80, v81
	v_add_f32_e32 v19, v48, v53
	v_add_f32_e32 v48, v89, v88
	v_add_f32_e32 v53, v90, v91
	v_add_f32_e32 v20, v48, v53
	ds_bpermute_b32 v21, v202, v13
	ds_bpermute_b32 v22, v202, v14
	ds_bpermute_b32 v23, v202, v15
	ds_bpermute_b32 v24, v202, v16
	ds_bpermute_b32 v25, v202, v17
	ds_bpermute_b32 v26, v202, v18
	ds_bpermute_b32 v37, v202, v19
	ds_bpermute_b32 v43, v202, v20
	s_waitcnt lgkmcnt(0)
	v_add_f32_e32 v13, v13, v21
	v_add_f32_e32 v14, v14, v22
	v_add_f32_e32 v15, v15, v23
	v_add_f32_e32 v16, v16, v24
	v_add_f32_e32 v17, v17, v25
	v_add_f32_e32 v18, v18, v26
	v_add_f32_e32 v19, v19, v37
	v_add_f32_e32 v20, v20, v43
	ds_bpermute_b32 v21, v203, v13
	ds_bpermute_b32 v22, v203, v14
	ds_bpermute_b32 v23, v203, v15
	ds_bpermute_b32 v24, v203, v16
	ds_bpermute_b32 v25, v203, v17
	ds_bpermute_b32 v26, v203, v18
	ds_bpermute_b32 v37, v203, v19
	ds_bpermute_b32 v43, v203, v20
	s_waitcnt lgkmcnt(0)
	v_add_f32_e32 v13, v13, v21
	v_add_f32_e32 v14, v14, v22
	v_add_f32_e32 v15, v15, v23
	v_add_f32_e32 v16, v16, v24
	v_add_f32_e32 v17, v17, v25
	v_add_f32_e32 v18, v18, v26
	v_add_f32_e32 v19, v19, v37
	v_add_f32_e32 v20, v20, v43
	ds_bpermute_b32 v21, v204, v13
	ds_bpermute_b32 v22, v204, v14
	ds_bpermute_b32 v23, v204, v15
	ds_bpermute_b32 v24, v204, v16
	ds_bpermute_b32 v25, v204, v17
	ds_bpermute_b32 v26, v204, v18
	ds_bpermute_b32 v37, v204, v19
	ds_bpermute_b32 v43, v204, v20
	s_waitcnt lgkmcnt(0)
	v_add_f32_e32 v13, v13, v21
	v_add_f32_e32 v14, v14, v22
	v_add_f32_e32 v15, v15, v23
	v_add_f32_e32 v16, v16, v24
	v_add_f32_e32 v17, v17, v25
	v_add_f32_e32 v18, v18, v26
	v_add_f32_e32 v19, v19, v37
	v_add_f32_e32 v20, v20, v43
	ds_bpermute_b32 v21, v205, v13
	ds_bpermute_b32 v22, v205, v14
	ds_bpermute_b32 v23, v205, v15
	ds_bpermute_b32 v24, v205, v16
	ds_bpermute_b32 v25, v205, v17
	ds_bpermute_b32 v26, v205, v18
	ds_bpermute_b32 v37, v205, v19
	ds_bpermute_b32 v43, v205, v20
	s_waitcnt lgkmcnt(0)
	v_add_f32_e32 v13, v13, v21
	v_add_f32_e32 v14, v14, v22
	v_add_f32_e32 v15, v15, v23
	v_add_f32_e32 v16, v16, v24
	v_add_f32_e32 v17, v17, v25
	v_add_f32_e32 v18, v18, v26
	v_add_f32_e32 v19, v19, v37
	v_add_f32_e32 v20, v20, v43
	ds_bpermute_b32 v21, v206, v13
	ds_bpermute_b32 v22, v206, v14
	ds_bpermute_b32 v23, v206, v15
	ds_bpermute_b32 v24, v206, v16
	ds_bpermute_b32 v25, v206, v17
	ds_bpermute_b32 v26, v206, v18
	ds_bpermute_b32 v37, v206, v19
	ds_bpermute_b32 v43, v206, v20
	s_waitcnt lgkmcnt(0)
	v_add_f32_e32 v13, v13, v21
	v_add_f32_e32 v14, v14, v22
	v_add_f32_e32 v15, v15, v23
	v_add_f32_e32 v16, v16, v24
	v_add_f32_e32 v17, v17, v25
	v_add_f32_e32 v18, v18, v26
	v_add_f32_e32 v19, v19, v37
	v_add_f32_e32 v20, v20, v43
	ds_bpermute_b32 v21, v11, v13
	ds_bpermute_b32 v22, v11, v14
	ds_bpermute_b32 v23, v11, v15
	ds_bpermute_b32 v24, v11, v16
	ds_bpermute_b32 v25, v11, v17
	ds_bpermute_b32 v26, v11, v18
	ds_bpermute_b32 v37, v11, v19
	ds_bpermute_b32 v43, v11, v20
	s_waitcnt lgkmcnt(0)
	v_add_f32_e32 v13, v13, v21
	v_add_f32_e32 v14, v14, v22
	v_add_f32_e32 v15, v15, v23
	v_add_f32_e32 v16, v16, v24
	v_add_f32_e32 v17, v17, v25
	v_add_f32_e32 v18, v18, v26
	v_add_f32_e32 v19, v19, v37
	v_add_f32_e32 v20, v20, v43
	v_fmamk_f32 v28, v13, 0xbb800000, v28
	v_fmamk_f32 v29, v13, 0xbb800000, v29
	v_fmamk_f32 v30, v13, 0xbb800000, v30
	v_fmamk_f32 v31, v13, 0xbb800000, v31
	v_fmamk_f32 v32, v14, 0xbb800000, v32
	v_fmamk_f32 v33, v14, 0xbb800000, v33
	v_fmamk_f32 v34, v14, 0xbb800000, v34
	v_fmamk_f32 v35, v14, 0xbb800000, v35
	v_fmamk_f32 v38, v15, 0xbb800000, v38
	v_fmamk_f32 v39, v15, 0xbb800000, v39
	v_fmamk_f32 v40, v15, 0xbb800000, v40
	v_fmamk_f32 v41, v15, 0xbb800000, v41
	v_fmamk_f32 v44, v16, 0xbb800000, v44
	v_fmamk_f32 v45, v16, 0xbb800000, v45
	v_fmamk_f32 v46, v16, 0xbb800000, v46
	v_fmamk_f32 v47, v16, 0xbb800000, v47
	v_fmamk_f32 v54, v17, 0xbb800000, v54
	v_fmamk_f32 v55, v17, 0xbb800000, v55
	v_fmamk_f32 v56, v17, 0xbb800000, v56
	v_fmamk_f32 v57, v17, 0xbb800000, v57
	v_fmamk_f32 v62, v18, 0xbb800000, v62
	v_fmamk_f32 v63, v18, 0xbb800000, v63
	v_fmamk_f32 v64, v18, 0xbb800000, v64
	v_fmamk_f32 v65, v18, 0xbb800000, v65
	v_fmamk_f32 v78, v19, 0xbb800000, v78
	v_fmamk_f32 v79, v19, 0xbb800000, v79
	v_fmamk_f32 v80, v19, 0xbb800000, v80
	v_fmamk_f32 v81, v19, 0xbb800000, v81
	v_fmamk_f32 v88, v20, 0xbb800000, v88
	v_fmamk_f32 v89, v20, 0xbb800000, v89
	v_fmamk_f32 v90, v20, 0xbb800000, v90
	v_fmamk_f32 v91, v20, 0xbb800000, v91
	v_mul_f32_e32 v48, v29, v29
	v_mul_f32_e32 v53, v30, v30
	v_mul_f32_e32 v21, v28, v28
	v_mul_f32_e32 v13, v31, v31
	v_add_f32_e32 v48, v48, v21
	v_add_f32_e32 v53, v53, v13
	v_add_f32_e32 v13, v48, v53
	v_mul_f32_e32 v48, v33, v33
	v_mul_f32_e32 v53, v34, v34
	v_mul_f32_e32 v22, v32, v32
	v_mul_f32_e32 v14, v35, v35
	v_add_f32_e32 v48, v48, v22
	v_add_f32_e32 v53, v53, v14
	v_add_f32_e32 v14, v48, v53
	v_mul_f32_e32 v48, v39, v39
	v_mul_f32_e32 v53, v40, v40
	v_mul_f32_e32 v23, v38, v38
	v_mul_f32_e32 v15, v41, v41
	v_add_f32_e32 v48, v48, v23
	v_add_f32_e32 v53, v53, v15
	v_add_f32_e32 v15, v48, v53
	v_mul_f32_e32 v48, v45, v45
	v_mul_f32_e32 v53, v46, v46
	v_mul_f32_e32 v24, v44, v44
	v_mul_f32_e32 v16, v47, v47
	v_add_f32_e32 v48, v48, v24
	v_add_f32_e32 v53, v53, v16
	v_add_f32_e32 v16, v48, v53
	v_mul_f32_e32 v48, v55, v55
	v_mul_f32_e32 v53, v56, v56
	v_mul_f32_e32 v25, v54, v54
	v_mul_f32_e32 v17, v57, v57
	v_add_f32_e32 v48, v48, v25
	v_add_f32_e32 v53, v53, v17
	v_add_f32_e32 v17, v48, v53
	v_mul_f32_e32 v48, v63, v63
	v_mul_f32_e32 v53, v64, v64
	v_mul_f32_e32 v26, v62, v62
	v_mul_f32_e32 v18, v65, v65
	v_add_f32_e32 v48, v48, v26
	v_add_f32_e32 v53, v53, v18
	v_add_f32_e32 v18, v48, v53
	v_mul_f32_e32 v48, v79, v79
	v_mul_f32_e32 v53, v80, v80
	v_mul_f32_e32 v37, v78, v78
	v_mul_f32_e32 v19, v81, v81
	v_add_f32_e32 v48, v48, v37
	v_add_f32_e32 v53, v53, v19
	v_add_f32_e32 v19, v48, v53
	v_mul_f32_e32 v48, v89, v89
	v_mul_f32_e32 v53, v90, v90
	v_mul_f32_e32 v43, v88, v88
	v_mul_f32_e32 v20, v91, v91
	v_add_f32_e32 v48, v48, v43
	v_add_f32_e32 v53, v53, v20
	v_add_f32_e32 v20, v48, v53
	ds_bpermute_b32 v21, v202, v13
	ds_bpermute_b32 v22, v202, v14
	ds_bpermute_b32 v23, v202, v15
	ds_bpermute_b32 v24, v202, v16
	ds_bpermute_b32 v25, v202, v17
	ds_bpermute_b32 v26, v202, v18
	ds_bpermute_b32 v37, v202, v19
	ds_bpermute_b32 v43, v202, v20
	s_waitcnt lgkmcnt(0)
	v_add_f32_e32 v13, v13, v21
	v_add_f32_e32 v14, v14, v22
	v_add_f32_e32 v15, v15, v23
	v_add_f32_e32 v16, v16, v24
	v_add_f32_e32 v17, v17, v25
	v_add_f32_e32 v18, v18, v26
	v_add_f32_e32 v19, v19, v37
	v_add_f32_e32 v20, v20, v43
	ds_bpermute_b32 v21, v203, v13
	ds_bpermute_b32 v22, v203, v14
	ds_bpermute_b32 v23, v203, v15
	ds_bpermute_b32 v24, v203, v16
	ds_bpermute_b32 v25, v203, v17
	ds_bpermute_b32 v26, v203, v18
	ds_bpermute_b32 v37, v203, v19
	ds_bpermute_b32 v43, v203, v20
	s_waitcnt lgkmcnt(0)
	v_add_f32_e32 v13, v13, v21
	v_add_f32_e32 v14, v14, v22
	v_add_f32_e32 v15, v15, v23
	v_add_f32_e32 v16, v16, v24
	v_add_f32_e32 v17, v17, v25
	v_add_f32_e32 v18, v18, v26
	v_add_f32_e32 v19, v19, v37
	v_add_f32_e32 v20, v20, v43
	ds_bpermute_b32 v21, v204, v13
	ds_bpermute_b32 v22, v204, v14
	ds_bpermute_b32 v23, v204, v15
	ds_bpermute_b32 v24, v204, v16
	ds_bpermute_b32 v25, v204, v17
	ds_bpermute_b32 v26, v204, v18
	ds_bpermute_b32 v37, v204, v19
	ds_bpermute_b32 v43, v204, v20
	s_waitcnt lgkmcnt(0)
	v_add_f32_e32 v13, v13, v21
	v_add_f32_e32 v14, v14, v22
	v_add_f32_e32 v15, v15, v23
	v_add_f32_e32 v16, v16, v24
	v_add_f32_e32 v17, v17, v25
	v_add_f32_e32 v18, v18, v26
	v_add_f32_e32 v19, v19, v37
	v_add_f32_e32 v20, v20, v43
	ds_bpermute_b32 v21, v205, v13
	ds_bpermute_b32 v22, v205, v14
	ds_bpermute_b32 v23, v205, v15
	ds_bpermute_b32 v24, v205, v16
	ds_bpermute_b32 v25, v205, v17
	ds_bpermute_b32 v26, v205, v18
	ds_bpermute_b32 v37, v205, v19
	ds_bpermute_b32 v43, v205, v20
	s_waitcnt lgkmcnt(0)
	v_add_f32_e32 v13, v13, v21
	v_add_f32_e32 v14, v14, v22
	v_add_f32_e32 v15, v15, v23
	v_add_f32_e32 v16, v16, v24
	v_add_f32_e32 v17, v17, v25
	v_add_f32_e32 v18, v18, v26
	v_add_f32_e32 v19, v19, v37
	v_add_f32_e32 v20, v20, v43
	ds_bpermute_b32 v21, v206, v13
	ds_bpermute_b32 v22, v206, v14
	ds_bpermute_b32 v23, v206, v15
	ds_bpermute_b32 v24, v206, v16
	ds_bpermute_b32 v25, v206, v17
	ds_bpermute_b32 v26, v206, v18
	ds_bpermute_b32 v37, v206, v19
	ds_bpermute_b32 v43, v206, v20
	s_waitcnt lgkmcnt(0)
	v_add_f32_e32 v13, v13, v21
	v_add_f32_e32 v14, v14, v22
	v_add_f32_e32 v15, v15, v23
	v_add_f32_e32 v16, v16, v24
	v_add_f32_e32 v17, v17, v25
	v_add_f32_e32 v18, v18, v26
	v_add_f32_e32 v19, v19, v37
	v_add_f32_e32 v20, v20, v43
	ds_bpermute_b32 v21, v11, v13
	ds_bpermute_b32 v22, v11, v14
	ds_bpermute_b32 v23, v11, v15
	ds_bpermute_b32 v24, v11, v16
	ds_bpermute_b32 v25, v11, v17
	ds_bpermute_b32 v26, v11, v18
	ds_bpermute_b32 v37, v11, v19
	ds_bpermute_b32 v43, v11, v20
	s_waitcnt lgkmcnt(0)
	v_add_f32_e32 v13, v13, v21
	v_add_f32_e32 v14, v14, v22
	v_add_f32_e32 v15, v15, v23
	v_add_f32_e32 v16, v16, v24
	v_add_f32_e32 v17, v17, v25
	v_add_f32_e32 v18, v18, v26
	v_add_f32_e32 v19, v19, v37
	v_add_f32_e32 v20, v20, v43
	v_fmamk_f32 v13, v13, 0x3b800000, v228
	v_fmamk_f32 v14, v14, 0x3b800000, v228
	v_fmamk_f32 v15, v15, 0x3b800000, v228
	v_fmamk_f32 v16, v16, 0x3b800000, v228
	v_fmamk_f32 v17, v17, 0x3b800000, v228
	v_fmamk_f32 v18, v18, 0x3b800000, v228
	v_fmamk_f32 v19, v19, 0x3b800000, v228
	v_fmamk_f32 v20, v20, 0x3b800000, v228
	v_rsq_f32_e32 v13, v13
	v_rsq_f32_e32 v14, v14
	v_rsq_f32_e32 v15, v15
	v_rsq_f32_e32 v16, v16
	v_rsq_f32_e32 v17, v17
	v_rsq_f32_e32 v18, v18
	v_rsq_f32_e32 v19, v19
	v_rsq_f32_e32 v20, v20
	s_nop 0
	v_mul_f32_e32 v28, v28, v13
	v_mul_f32_e32 v29, v29, v13
	v_mul_f32_e32 v30, v30, v13
	v_mul_f32_e32 v31, v31, v13
	v_mul_f32_e32 v32, v32, v14
	v_mul_f32_e32 v33, v33, v14
	v_mul_f32_e32 v34, v34, v14
	v_mul_f32_e32 v35, v35, v14
	v_mul_f32_e32 v38, v38, v15
	v_mul_f32_e32 v39, v39, v15
	v_mul_f32_e32 v40, v40, v15
	v_mul_f32_e32 v41, v41, v15
	v_mul_f32_e32 v44, v44, v16
	v_mul_f32_e32 v45, v45, v16
	v_mul_f32_e32 v46, v46, v16
	v_mul_f32_e32 v47, v47, v16
	v_mul_f32_e32 v54, v54, v17
	v_mul_f32_e32 v55, v55, v17
	v_mul_f32_e32 v56, v56, v17
	v_mul_f32_e32 v57, v57, v17
	v_mul_f32_e32 v62, v62, v18
	v_mul_f32_e32 v63, v63, v18
	v_mul_f32_e32 v64, v64, v18
	v_mul_f32_e32 v65, v65, v18
	v_mul_f32_e32 v78, v78, v19
	v_mul_f32_e32 v79, v79, v19
	v_mul_f32_e32 v80, v80, v19
	v_mul_f32_e32 v81, v81, v19
	v_mul_f32_e32 v88, v88, v20
	v_mul_f32_e32 v89, v89, v20
	v_mul_f32_e32 v90, v90, v20
	v_mul_f32_e32 v91, v91, v20
	v_fma_f32 v28, v0, v28, v4
	v_fma_f32 v29, v1, v29, v5
	v_fma_f32 v30, v2, v30, v6
	v_fma_f32 v31, v3, v31, v7
	v_fma_f32 v32, v0, v32, v4
	v_fma_f32 v33, v1, v33, v5
	v_fma_f32 v34, v2, v34, v6
	v_fma_f32 v35, v3, v35, v7
	v_fma_f32 v38, v0, v38, v4
	v_fma_f32 v39, v1, v39, v5
	v_fma_f32 v40, v2, v40, v6
	v_fma_f32 v41, v3, v41, v7
	v_fma_f32 v44, v0, v44, v4
	v_fma_f32 v45, v1, v45, v5
	v_fma_f32 v46, v2, v46, v6
	v_fma_f32 v47, v3, v47, v7
	v_fma_f32 v54, v0, v54, v4
	v_fma_f32 v55, v1, v55, v5
	v_fma_f32 v56, v2, v56, v6
	v_fma_f32 v57, v3, v57, v7
	v_fma_f32 v62, v0, v62, v4
	v_fma_f32 v63, v1, v63, v5
	v_fma_f32 v64, v2, v64, v6
	v_fma_f32 v65, v3, v65, v7
	v_fma_f32 v78, v0, v78, v4
	v_fma_f32 v79, v1, v79, v5
	v_fma_f32 v80, v2, v80, v6
	v_fma_f32 v81, v3, v81, v7
	v_fma_f32 v88, v0, v88, v4
	v_fma_f32 v89, v1, v89, v5
	v_fma_f32 v90, v2, v90, v6
	v_fma_f32 v91, v3, v91, v7
	v_mul_f32_e32 v21, 0xbfb8aa3b, v28
	v_mul_f32_e32 v22, 0xbfb8aa3b, v29
	v_mul_f32_e32 v23, 0xbfb8aa3b, v30
	v_mul_f32_e32 v24, 0xbfb8aa3b, v31
	v_mul_f32_e32 v25, 0xbfb8aa3b, v32
	v_mul_f32_e32 v26, 0xbfb8aa3b, v33
	v_mul_f32_e32 v37, 0xbfb8aa3b, v34
	v_mul_f32_e32 v43, 0xbfb8aa3b, v35
	v_mul_f32_e32 v13, 0xbfb8aa3b, v38
	v_mul_f32_e32 v14, 0xbfb8aa3b, v39
	v_mul_f32_e32 v15, 0xbfb8aa3b, v40
	v_mul_f32_e32 v16, 0xbfb8aa3b, v41
	v_mul_f32_e32 v17, 0xbfb8aa3b, v44
	v_mul_f32_e32 v18, 0xbfb8aa3b, v45
	v_mul_f32_e32 v19, 0xbfb8aa3b, v46
	v_mul_f32_e32 v20, 0xbfb8aa3b, v47
	v_exp_f32_e32 v21, v21
	v_exp_f32_e32 v22, v22
	v_exp_f32_e32 v23, v23
	v_exp_f32_e32 v24, v24
	v_exp_f32_e32 v25, v25
	v_exp_f32_e32 v26, v26
	v_exp_f32_e32 v37, v37
	v_exp_f32_e32 v43, v43
	v_exp_f32_e32 v13, v13
	v_exp_f32_e32 v14, v14
	v_exp_f32_e32 v15, v15
	v_exp_f32_e32 v16, v16
	v_exp_f32_e32 v17, v17
	v_exp_f32_e32 v18, v18
	v_exp_f32_e32 v19, v19
	v_exp_f32_e32 v20, v20
	v_add_f32_e32 v21, 1.0, v21
	v_add_f32_e32 v22, 1.0, v22
	v_add_f32_e32 v23, 1.0, v23
	v_add_f32_e32 v24, 1.0, v24
	v_add_f32_e32 v25, 1.0, v25
	v_add_f32_e32 v26, 1.0, v26
	v_add_f32_e32 v37, 1.0, v37
	v_add_f32_e32 v43, 1.0, v43
	v_add_f32_e32 v13, 1.0, v13
	v_add_f32_e32 v14, 1.0, v14
	v_add_f32_e32 v15, 1.0, v15
	v_add_f32_e32 v16, 1.0, v16
	v_add_f32_e32 v17, 1.0, v17
	v_add_f32_e32 v18, 1.0, v18
	v_add_f32_e32 v19, 1.0, v19
	v_add_f32_e32 v20, 1.0, v20
	v_rcp_f32_e32 v21, v21
	v_rcp_f32_e32 v22, v22
	v_rcp_f32_e32 v23, v23
	v_rcp_f32_e32 v24, v24
	v_rcp_f32_e32 v25, v25
	v_rcp_f32_e32 v26, v26
	v_rcp_f32_e32 v37, v37
	v_rcp_f32_e32 v43, v43
	v_rcp_f32_e32 v13, v13
	v_rcp_f32_e32 v14, v14
	v_rcp_f32_e32 v15, v15
	v_rcp_f32_e32 v16, v16
	v_rcp_f32_e32 v17, v17
	v_rcp_f32_e32 v18, v18
	v_rcp_f32_e32 v19, v19
	v_rcp_f32_e32 v20, v20
	v_mul_f32_e32 v28, v28, v21
	v_mul_f32_e32 v29, v29, v22
	v_mul_f32_e32 v30, v30, v23
	v_mul_f32_e32 v31, v31, v24
	v_mul_f32_e32 v32, v32, v25
	v_mul_f32_e32 v33, v33, v26
	v_mul_f32_e32 v34, v34, v37
	v_mul_f32_e32 v35, v35, v43
	v_mul_f32_e32 v38, v38, v13
	v_mul_f32_e32 v39, v39, v14
	v_mul_f32_e32 v40, v40, v15
	v_mul_f32_e32 v41, v41, v16
	v_mul_f32_e32 v44, v44, v17
	v_mul_f32_e32 v45, v45, v18
	v_mul_f32_e32 v46, v46, v19
	v_mul_f32_e32 v47, v47, v20
	v_mul_f32_e32 v21, 0xbfb8aa3b, v54
	v_mul_f32_e32 v22, 0xbfb8aa3b, v55
	v_mul_f32_e32 v23, 0xbfb8aa3b, v56
	v_mul_f32_e32 v24, 0xbfb8aa3b, v57
	v_mul_f32_e32 v25, 0xbfb8aa3b, v62
	v_mul_f32_e32 v26, 0xbfb8aa3b, v63
	v_mul_f32_e32 v37, 0xbfb8aa3b, v64
	v_mul_f32_e32 v43, 0xbfb8aa3b, v65
	v_mul_f32_e32 v13, 0xbfb8aa3b, v78
	v_mul_f32_e32 v14, 0xbfb8aa3b, v79
	v_mul_f32_e32 v15, 0xbfb8aa3b, v80
	v_mul_f32_e32 v16, 0xbfb8aa3b, v81
	v_mul_f32_e32 v17, 0xbfb8aa3b, v88
	v_mul_f32_e32 v18, 0xbfb8aa3b, v89
	v_mul_f32_e32 v19, 0xbfb8aa3b, v90
	v_mul_f32_e32 v20, 0xbfb8aa3b, v91
	v_exp_f32_e32 v21, v21
	v_exp_f32_e32 v22, v22
	v_exp_f32_e32 v23, v23
	v_exp_f32_e32 v24, v24
	v_exp_f32_e32 v25, v25
	v_exp_f32_e32 v26, v26
	v_exp_f32_e32 v37, v37
	v_exp_f32_e32 v43, v43
	v_exp_f32_e32 v13, v13
	v_exp_f32_e32 v14, v14
	v_exp_f32_e32 v15, v15
	v_exp_f32_e32 v16, v16
	v_exp_f32_e32 v17, v17
	v_exp_f32_e32 v18, v18
	v_exp_f32_e32 v19, v19
	v_exp_f32_e32 v20, v20
	v_add_f32_e32 v21, 1.0, v21
	v_add_f32_e32 v22, 1.0, v22
	v_add_f32_e32 v23, 1.0, v23
	v_add_f32_e32 v24, 1.0, v24
	v_add_f32_e32 v25, 1.0, v25
	v_add_f32_e32 v26, 1.0, v26
	v_add_f32_e32 v37, 1.0, v37
	v_add_f32_e32 v43, 1.0, v43
	v_add_f32_e32 v13, 1.0, v13
	v_add_f32_e32 v14, 1.0, v14
	v_add_f32_e32 v15, 1.0, v15
	v_add_f32_e32 v16, 1.0, v16
	v_add_f32_e32 v17, 1.0, v17
	v_add_f32_e32 v18, 1.0, v18
	v_add_f32_e32 v19, 1.0, v19
	v_add_f32_e32 v20, 1.0, v20
	v_rcp_f32_e32 v21, v21
	v_rcp_f32_e32 v22, v22
	v_rcp_f32_e32 v23, v23
	v_rcp_f32_e32 v24, v24
	v_rcp_f32_e32 v25, v25
	v_rcp_f32_e32 v26, v26
	v_rcp_f32_e32 v37, v37
	v_rcp_f32_e32 v43, v43
	v_rcp_f32_e32 v13, v13
	v_rcp_f32_e32 v14, v14
	v_rcp_f32_e32 v15, v15
	v_rcp_f32_e32 v16, v16
	v_rcp_f32_e32 v17, v17
	v_rcp_f32_e32 v18, v18
	v_rcp_f32_e32 v19, v19
	v_rcp_f32_e32 v20, v20
	v_mul_f32_e32 v54, v54, v21
	v_mul_f32_e32 v55, v55, v22
	v_mul_f32_e32 v56, v56, v23
	v_mul_f32_e32 v57, v57, v24
	v_mul_f32_e32 v62, v62, v25
	v_mul_f32_e32 v63, v63, v26
	v_mul_f32_e32 v64, v64, v37
	v_mul_f32_e32 v65, v65, v43
	v_mul_f32_e32 v78, v78, v13
	v_mul_f32_e32 v79, v79, v14
	v_mul_f32_e32 v80, v80, v15
	v_mul_f32_e32 v81, v81, v16
	v_mul_f32_e32 v88, v88, v17
	v_mul_f32_e32 v89, v89, v18
	v_mul_f32_e32 v90, v90, v19
	v_mul_f32_e32 v91, v91, v20
	v_cvt_pk_bf16_f32 v28, v28, v29
	v_cvt_pk_bf16_f32 v29, v30, v31
	v_cvt_pk_bf16_f32 v32, v32, v33
	v_cvt_pk_bf16_f32 v33, v34, v35
	v_cvt_pk_bf16_f32 v38, v38, v39
	v_cvt_pk_bf16_f32 v39, v40, v41
	v_cvt_pk_bf16_f32 v44, v44, v45
	v_cvt_pk_bf16_f32 v45, v46, v47
	v_cvt_pk_bf16_f32 v54, v54, v55
	v_cvt_pk_bf16_f32 v55, v56, v57
	v_cvt_pk_bf16_f32 v62, v62, v63
	v_cvt_pk_bf16_f32 v63, v64, v65
	v_cvt_pk_bf16_f32 v78, v78, v79
	v_cvt_pk_bf16_f32 v79, v80, v81
	v_cvt_pk_bf16_f32 v88, v88, v89
	v_cvt_pk_bf16_f32 v89, v90, v91
	global_store_dwordx2 v[8:9], v[28:29], off
	v_lshl_add_u64 v[8:9], v[8:9], 0, s[8:9]
	global_store_dwordx2 v[8:9], v[32:33], off
	v_lshl_add_u64 v[8:9], v[8:9], 0, s[8:9]
	global_store_dwordx2 v[8:9], v[38:39], off
	v_lshl_add_u64 v[8:9], v[8:9], 0, s[8:9]
	global_store_dwordx2 v[8:9], v[44:45], off
	v_lshl_add_u64 v[8:9], v[8:9], 0, s[8:9]
	global_store_dwordx2 v[8:9], v[54:55], off
	v_lshl_add_u64 v[8:9], v[8:9], 0, s[8:9]
	global_store_dwordx2 v[8:9], v[62:63], off
	v_lshl_add_u64 v[8:9], v[8:9], 0, s[8:9]
	global_store_dwordx2 v[8:9], v[78:79], off
	v_lshl_add_u64 v[8:9], v[8:9], 0, s[8:9]
	global_store_dwordx2 v[8:9], v[88:89], off
	v_lshl_add_u64 v[8:9], v[8:9], 0, s[8:9]
	s_add_i32 s18, s18, s17
	s_cmp_lt_u32 s18, s16
	s_barrier
	s_cbranch_scc1 .LBB0_988
